# GEMM loops: s_setprio 1 issued before the pre-compute s_barrier (wave wakes prioritized); plus attention staging prefetch
# baseline (speedup 1.0000x reference)
.LBB0_180:
	s_add_u32 s62, s60, 0xfffc0080
	s_addc_u32 s63, s61, -1
	s_add_i32 s86, 0, 0x10000
	s_cmp_eq_u32 s85, 12
	s_cselect_b32 vcc_hi, s47, s63
	s_cselect_b32 vcc_lo, s82, s62
	v_add_u32_e32 v142, s86, v145
	s_cselect_b32 s63, s21, s84
	s_cselect_b32 s62, s83, s89
	s_add_i32 s92, 0, 0x14000
	ds_read_b128 v[138:141], v142
	ds_read_b128 v[172:175], v142 offset:1024
	ds_read_b128 v[176:179], v142 offset:2048
	ds_read_b128 v[180:183], v142 offset:3072
	v_add_u32_e32 v142, s92, v145
	ds_read_b128 v[184:187], v142
	ds_read_b128 v[188:191], v142 offset:1024
	ds_read_b128 v[192:195], v142 offset:2048
	ds_read_b128 v[196:199], v142 offset:3072
	v_lshl_add_u64 v[142:143], s[60:61], 0, v[136:137]
	s_add_i32 m0, s68, 0xc000
	ds_read_b128 v[210:213], v148
	ds_read_b128 v[214:217], v148 offset:1024
	ds_read_b128 v[218:221], v148 offset:2048
	ds_read_b128 v[224:227], v148 offset:3072
	ds_read_b128 v[228:231], v148 offset:4096
	ds_read_b128 v[232:235], v148 offset:5120
	ds_read_b128 v[236:239], v148 offset:6144
	ds_read_b128 v[240:243], v148 offset:7168
	global_load_lds_dwordx4 v[142:143], off
	v_lshl_add_u64 v[142:143], s[60:61], 0, v[134:135]
	s_add_i32 m0, s68, 0xe000
	s_nop 0
	global_load_lds_dwordx4 v[142:143], off
	s_waitcnt vmcnt(8)
	s_waitcnt lgkmcnt(0)
	s_setprio 1
	s_barrier
	s_waitcnt lgkmcnt(0)
	v_mfma_f32_16x16x32_bf16 v[124:127], v[138:141], v[210:213], v[124:127]
	v_mfma_f32_16x16x32_bf16 v[116:119], v[176:179], v[210:213], v[116:119]
	v_mfma_f32_16x16x32_bf16 v[108:111], v[138:141], v[218:221], v[108:111]
	v_mfma_f32_16x16x32_bf16 v[100:103], v[176:179], v[218:221], v[100:103]
	v_mfma_f32_16x16x32_bf16 v[92:95], v[138:141], v[228:231], v[92:95]
	v_mfma_f32_16x16x32_bf16 v[84:87], v[176:179], v[228:231], v[84:87]
	v_mfma_f32_16x16x32_bf16 v[76:79], v[138:141], v[236:239], v[76:79]
	v_mfma_f32_16x16x32_bf16 v[68:71], v[176:179], v[236:239], v[68:71]
	v_mfma_f32_16x16x32_bf16 v[124:127], v[172:175], v[214:217], v[124:127]
	v_mfma_f32_16x16x32_bf16 v[116:119], v[180:183], v[214:217], v[116:119]
	v_mfma_f32_16x16x32_bf16 v[108:111], v[172:175], v[224:227], v[108:111]
	v_mfma_f32_16x16x32_bf16 v[100:103], v[180:183], v[224:227], v[100:103]
	v_mfma_f32_16x16x32_bf16 v[92:95], v[172:175], v[232:235], v[92:95]
	v_mfma_f32_16x16x32_bf16 v[84:87], v[180:183], v[232:235], v[84:87]
	v_mfma_f32_16x16x32_bf16 v[76:79], v[172:175], v[240:243], v[76:79]
	v_mfma_f32_16x16x32_bf16 v[68:71], v[180:183], v[240:243], v[68:71]
	s_setprio 0
	s_setprio 1
	v_mfma_f32_16x16x32_bf16 v[120:123], v[184:187], v[210:213], v[120:123]
	v_mfma_f32_16x16x32_bf16 v[112:115], v[192:195], v[210:213], v[112:115]
	v_mfma_f32_16x16x32_bf16 v[104:107], v[184:187], v[218:221], v[104:107]
	v_mfma_f32_16x16x32_bf16 v[96:99], v[192:195], v[218:221], v[96:99]
	v_mfma_f32_16x16x32_bf16 v[88:91], v[184:187], v[228:231], v[88:91]
	v_mfma_f32_16x16x32_bf16 v[80:83], v[192:195], v[228:231], v[80:83]
	v_mfma_f32_16x16x32_bf16 v[72:75], v[184:187], v[236:239], v[72:75]
	v_mfma_f32_16x16x32_bf16 v[64:67], v[192:195], v[236:239], v[64:67]
	v_mfma_f32_16x16x32_bf16 v[120:123], v[188:191], v[214:217], v[120:123]
	v_mfma_f32_16x16x32_bf16 v[112:115], v[196:199], v[214:217], v[112:115]
	v_mfma_f32_16x16x32_bf16 v[104:107], v[188:191], v[224:227], v[104:107]
	v_mfma_f32_16x16x32_bf16 v[96:99], v[196:199], v[224:227], v[96:99]
	v_mfma_f32_16x16x32_bf16 v[88:91], v[188:191], v[232:235], v[88:91]
	v_mfma_f32_16x16x32_bf16 v[80:83], v[196:199], v[232:235], v[80:83]
	v_mfma_f32_16x16x32_bf16 v[72:75], v[188:191], v[240:243], v[72:75]
	v_mfma_f32_16x16x32_bf16 v[64:67], v[196:199], v[240:243], v[64:67]
	s_setprio 0
	s_barrier
	s_add_i32 s86, s86, s67
	v_lshl_add_u64 v[142:143], s[62:63], 0, v[152:153]
	s_mov_b32 m0, s86
	ds_read_b128 v[210:213], v148 offset:16384
	ds_read_b128 v[214:217], v148 offset:17408
	ds_read_b128 v[218:221], v148 offset:18432
	ds_read_b128 v[224:227], v148 offset:19456
	ds_read_b128 v[228:231], v148 offset:20480
	ds_read_b128 v[232:235], v148 offset:21504
	ds_read_b128 v[236:239], v148 offset:22528
	ds_read_b128 v[240:243], v148 offset:23552
	global_load_lds_dwordx4 v[142:143], off
	s_add_i32 m0, s86, 0x2000
	s_add_u32 s86, s62, 0x40000
	v_lshl_add_u64 v[150:151], s[62:63], 0, v[128:129]
	s_addc_u32 s87, s63, 0
	s_add_i32 s92, s92, s67
	global_load_lds_dwordx4 v[150:151], off
	v_lshl_add_u64 v[244:245], s[86:87], 0, v[152:153]
	s_mov_b32 m0, s92
	v_lshl_add_u64 v[246:247], vcc, 0, v[130:131]
	global_load_lds_dwordx4 v[244:245], off
	v_lshl_add_u64 v[244:245], s[86:87], 0, v[128:129]
	s_add_i32 m0, s92, 0x2000
	s_nop 0
	global_load_lds_dwordx4 v[244:245], off
	v_lshl_add_u64 v[244:245], vcc, 0, v[132:133]
	s_mov_b32 m0, s68
	s_nop 0
	global_load_lds_dwordx4 v[244:245], off
	s_mov_b32 m0, s69
	s_nop 0
	global_load_lds_dwordx4 v[246:247], off
	s_waitcnt vmcnt(8)
	s_waitcnt lgkmcnt(0)
	s_setprio 1
	s_barrier
	s_waitcnt lgkmcnt(0)
	v_mfma_f32_16x16x32_bf16 v[60:63], v[138:141], v[210:213], v[60:63]
	v_mfma_f32_16x16x32_bf16 v[52:55], v[176:179], v[210:213], v[52:55]
	v_mfma_f32_16x16x32_bf16 v[44:47], v[138:141], v[218:221], v[44:47]
	v_mfma_f32_16x16x32_bf16 v[36:39], v[176:179], v[218:221], v[36:39]
	v_mfma_f32_16x16x32_bf16 v[28:31], v[138:141], v[228:231], v[28:31]
	v_mfma_f32_16x16x32_bf16 v[20:23], v[176:179], v[228:231], v[20:23]
	v_mfma_f32_16x16x32_bf16 v[12:15], v[138:141], v[236:239], v[12:15]
	v_mfma_f32_16x16x32_bf16 v[4:7], v[176:179], v[236:239], v[4:7]
	v_mfma_f32_16x16x32_bf16 v[60:63], v[172:175], v[214:217], v[60:63]
	v_mfma_f32_16x16x32_bf16 v[52:55], v[180:183], v[214:217], v[52:55]
	v_mfma_f32_16x16x32_bf16 v[44:47], v[172:175], v[224:227], v[44:47]
	v_mfma_f32_16x16x32_bf16 v[36:39], v[180:183], v[224:227], v[36:39]
	v_mfma_f32_16x16x32_bf16 v[28:31], v[172:175], v[232:235], v[28:31]
	v_mfma_f32_16x16x32_bf16 v[20:23], v[180:183], v[232:235], v[20:23]
	v_mfma_f32_16x16x32_bf16 v[12:15], v[172:175], v[240:243], v[12:15]
	v_mfma_f32_16x16x32_bf16 v[4:7], v[180:183], v[240:243], v[4:7]
	s_setprio 0
	s_setprio 1
	v_mfma_f32_16x16x32_bf16 v[56:59], v[184:187], v[210:213], v[56:59]
	v_mfma_f32_16x16x32_bf16 v[48:51], v[192:195], v[210:213], v[48:51]
	v_mfma_f32_16x16x32_bf16 v[40:43], v[184:187], v[218:221], v[40:43]
	v_mfma_f32_16x16x32_bf16 v[32:35], v[192:195], v[218:221], v[32:35]
	v_mfma_f32_16x16x32_bf16 v[24:27], v[184:187], v[228:231], v[24:27]
	v_mfma_f32_16x16x32_bf16 v[16:19], v[192:195], v[228:231], v[16:19]
	v_mfma_f32_16x16x32_bf16 v[8:11], v[184:187], v[236:239], v[8:11]
	v_mfma_f32_16x16x32_bf16 v[0:3], v[192:195], v[236:239], v[0:3]
	v_mfma_f32_16x16x32_bf16 v[56:59], v[188:191], v[214:217], v[56:59]
	v_mfma_f32_16x16x32_bf16 v[48:51], v[196:199], v[214:217], v[48:51]
	v_mfma_f32_16x16x32_bf16 v[40:43], v[188:191], v[224:227], v[40:43]
	v_mfma_f32_16x16x32_bf16 v[32:35], v[196:199], v[224:227], v[32:35]
	v_mfma_f32_16x16x32_bf16 v[24:27], v[188:191], v[232:235], v[24:27]
	v_mfma_f32_16x16x32_bf16 v[16:19], v[196:199], v[232:235], v[16:19]
	v_mfma_f32_16x16x32_bf16 v[8:11], v[188:191], v[240:243], v[8:11]
	v_mfma_f32_16x16x32_bf16 v[0:3], v[196:199], v[240:243], v[0:3]
	s_setprio 0
	s_barrier
	s_add_i32 s92, 0, 0x18000
	v_add_u32_e32 v149, s92, v145
	s_add_i32 s93, 0, 0x1c000
	ds_read_b128 v[138:141], v149
	ds_read_b128 v[172:175], v149 offset:1024
	ds_read_b128 v[176:179], v149 offset:2048
	ds_read_b128 v[180:183], v149 offset:3072
	v_add_u32_e32 v149, s93, v145
	ds_read_b128 v[184:187], v149
	ds_read_b128 v[188:191], v149 offset:1024
	ds_read_b128 v[192:195], v149 offset:2048
	ds_read_b128 v[196:199], v149 offset:3072
	s_add_u32 s86, vcc_lo, 0x40000
	s_addc_u32 s87, vcc_hi, 0
	s_mov_b32 m0, s74
	v_lshl_add_u64 v[248:249], s[86:87], 0, v[132:133]
	ds_read_b128 v[210:213], v148 offset:32768
	ds_read_b128 v[214:217], v148 offset:33792
	ds_read_b128 v[218:221], v148 offset:34816
	ds_read_b128 v[224:227], v148 offset:35840
	ds_read_b128 v[228:231], v148 offset:36864
	ds_read_b128 v[232:235], v148 offset:37888
	ds_read_b128 v[236:239], v148 offset:38912
	ds_read_b128 v[240:243], v148 offset:39936
	global_load_lds_dwordx4 v[248:249], off
	v_lshl_add_u64 v[248:249], s[86:87], 0, v[130:131]
	s_mov_b32 m0, s75
	s_nop 0
	global_load_lds_dwordx4 v[248:249], off
	s_waitcnt vmcnt(8)
	s_waitcnt lgkmcnt(0)
	s_setprio 1
	s_barrier
	s_waitcnt lgkmcnt(0)
	v_mfma_f32_16x16x32_bf16 v[124:127], v[138:141], v[210:213], v[124:127]
	v_mfma_f32_16x16x32_bf16 v[116:119], v[176:179], v[210:213], v[116:119]
	v_mfma_f32_16x16x32_bf16 v[108:111], v[138:141], v[218:221], v[108:111]
	v_mfma_f32_16x16x32_bf16 v[100:103], v[176:179], v[218:221], v[100:103]
	v_mfma_f32_16x16x32_bf16 v[92:95], v[138:141], v[228:231], v[92:95]
	v_mfma_f32_16x16x32_bf16 v[84:87], v[176:179], v[228:231], v[84:87]
	v_mfma_f32_16x16x32_bf16 v[76:79], v[138:141], v[236:239], v[76:79]
	v_mfma_f32_16x16x32_bf16 v[68:71], v[176:179], v[236:239], v[68:71]
	v_mfma_f32_16x16x32_bf16 v[124:127], v[172:175], v[214:217], v[124:127]
	v_mfma_f32_16x16x32_bf16 v[116:119], v[180:183], v[214:217], v[116:119]
	v_mfma_f32_16x16x32_bf16 v[108:111], v[172:175], v[224:227], v[108:111]
	v_mfma_f32_16x16x32_bf16 v[100:103], v[180:183], v[224:227], v[100:103]
	v_mfma_f32_16x16x32_bf16 v[92:95], v[172:175], v[232:235], v[92:95]
	v_mfma_f32_16x16x32_bf16 v[84:87], v[180:183], v[232:235], v[84:87]
	v_mfma_f32_16x16x32_bf16 v[76:79], v[172:175], v[240:243], v[76:79]
	v_mfma_f32_16x16x32_bf16 v[68:71], v[180:183], v[240:243], v[68:71]
	s_setprio 0
	s_setprio 1
	v_mfma_f32_16x16x32_bf16 v[120:123], v[184:187], v[210:213], v[120:123]
	v_mfma_f32_16x16x32_bf16 v[112:115], v[192:195], v[210:213], v[112:115]
	v_mfma_f32_16x16x32_bf16 v[104:107], v[184:187], v[218:221], v[104:107]
	v_mfma_f32_16x16x32_bf16 v[96:99], v[192:195], v[218:221], v[96:99]
	v_mfma_f32_16x16x32_bf16 v[88:91], v[184:187], v[228:231], v[88:91]
	v_mfma_f32_16x16x32_bf16 v[80:83], v[192:195], v[228:231], v[80:83]
	v_mfma_f32_16x16x32_bf16 v[72:75], v[184:187], v[236:239], v[72:75]
	v_mfma_f32_16x16x32_bf16 v[64:67], v[192:195], v[236:239], v[64:67]
	v_mfma_f32_16x16x32_bf16 v[120:123], v[188:191], v[214:217], v[120:123]
	v_mfma_f32_16x16x32_bf16 v[112:115], v[196:199], v[214:217], v[112:115]
	v_mfma_f32_16x16x32_bf16 v[104:107], v[188:191], v[224:227], v[104:107]
	v_mfma_f32_16x16x32_bf16 v[96:99], v[196:199], v[224:227], v[96:99]
	v_mfma_f32_16x16x32_bf16 v[88:91], v[188:191], v[232:235], v[88:91]
	v_mfma_f32_16x16x32_bf16 v[80:83], v[196:199], v[232:235], v[80:83]
	v_mfma_f32_16x16x32_bf16 v[72:75], v[188:191], v[240:243], v[72:75]
	v_mfma_f32_16x16x32_bf16 v[64:67], v[196:199], v[240:243], v[64:67]
	s_setprio 0
	s_barrier
	s_add_i32 s86, s92, s67
	v_lshl_add_u64 v[142:143], v[142:143], 0, s[22:23]
	s_mov_b32 m0, s86
	ds_read_b128 v[210:213], v148 offset:49152
	ds_read_b128 v[214:217], v148 offset:50176
	ds_read_b128 v[218:221], v148 offset:51200
	ds_read_b128 v[224:227], v148 offset:52224
	ds_read_b128 v[228:231], v148 offset:53248
	ds_read_b128 v[232:235], v148 offset:54272
	ds_read_b128 v[236:239], v148 offset:55296
	ds_read_b128 v[240:243], v148 offset:56320
	global_load_lds_dwordx4 v[142:143], off
	s_add_i32 m0, s86, 0x2000
	s_add_u32 s62, s62, 0x40080
	v_lshl_add_u64 v[142:143], v[150:151], 0, s[22:23]
	s_addc_u32 s63, s63, 0
	s_add_i32 s86, s93, s67
	global_load_lds_dwordx4 v[142:143], off
	v_lshl_add_u64 v[142:143], s[62:63], 0, v[152:153]
	s_mov_b32 m0, s86
	s_nop 0
	global_load_lds_dwordx4 v[142:143], off
	v_lshl_add_u64 v[142:143], s[62:63], 0, v[128:129]
	s_add_i32 m0, s86, 0x2000
	s_nop 0
	global_load_lds_dwordx4 v[142:143], off
	v_lshl_add_u64 v[142:143], v[244:245], 0, s[22:23]
	s_mov_b32 m0, s77
	s_nop 0
	global_load_lds_dwordx4 v[142:143], off
	v_lshl_add_u64 v[142:143], v[246:247], 0, s[22:23]
	s_mov_b32 m0, s78
	s_nop 0
	global_load_lds_dwordx4 v[142:143], off
	s_waitcnt vmcnt(8)
	s_waitcnt lgkmcnt(0)
	s_setprio 1
	s_barrier
	s_waitcnt lgkmcnt(0)
	v_mfma_f32_16x16x32_bf16 v[60:63], v[138:141], v[210:213], v[60:63]
	v_mfma_f32_16x16x32_bf16 v[52:55], v[176:179], v[210:213], v[52:55]
	v_mfma_f32_16x16x32_bf16 v[44:47], v[138:141], v[218:221], v[44:47]
	v_mfma_f32_16x16x32_bf16 v[36:39], v[176:179], v[218:221], v[36:39]
	v_mfma_f32_16x16x32_bf16 v[28:31], v[138:141], v[228:231], v[28:31]
	v_mfma_f32_16x16x32_bf16 v[20:23], v[176:179], v[228:231], v[20:23]
	v_mfma_f32_16x16x32_bf16 v[12:15], v[138:141], v[236:239], v[12:15]
	v_mfma_f32_16x16x32_bf16 v[4:7], v[176:179], v[236:239], v[4:7]
	v_mfma_f32_16x16x32_bf16 v[60:63], v[172:175], v[214:217], v[60:63]
	v_mfma_f32_16x16x32_bf16 v[52:55], v[180:183], v[214:217], v[52:55]
	v_mfma_f32_16x16x32_bf16 v[44:47], v[172:175], v[224:227], v[44:47]
	v_mfma_f32_16x16x32_bf16 v[36:39], v[180:183], v[224:227], v[36:39]
	v_mfma_f32_16x16x32_bf16 v[28:31], v[172:175], v[232:235], v[28:31]
	v_mfma_f32_16x16x32_bf16 v[20:23], v[180:183], v[232:235], v[20:23]
	v_mfma_f32_16x16x32_bf16 v[12:15], v[172:175], v[240:243], v[12:15]
	v_mfma_f32_16x16x32_bf16 v[4:7], v[180:183], v[240:243], v[4:7]
	s_setprio 0
	s_setprio 1
	v_mfma_f32_16x16x32_bf16 v[56:59], v[184:187], v[210:213], v[56:59]
	v_mfma_f32_16x16x32_bf16 v[48:51], v[192:195], v[210:213], v[48:51]
	v_mfma_f32_16x16x32_bf16 v[40:43], v[184:187], v[218:221], v[40:43]
	v_mfma_f32_16x16x32_bf16 v[32:35], v[192:195], v[218:221], v[32:35]
	v_mfma_f32_16x16x32_bf16 v[24:27], v[184:187], v[228:231], v[24:27]
	v_mfma_f32_16x16x32_bf16 v[16:19], v[192:195], v[228:231], v[16:19]
	v_mfma_f32_16x16x32_bf16 v[8:11], v[184:187], v[236:239], v[8:11]
	v_mfma_f32_16x16x32_bf16 v[0:3], v[192:195], v[236:239], v[0:3]
	v_mfma_f32_16x16x32_bf16 v[56:59], v[188:191], v[214:217], v[56:59]
	v_mfma_f32_16x16x32_bf16 v[48:51], v[196:199], v[214:217], v[48:51]
	v_mfma_f32_16x16x32_bf16 v[40:43], v[188:191], v[224:227], v[40:43]
	v_mfma_f32_16x16x32_bf16 v[32:35], v[196:199], v[224:227], v[32:35]
	v_mfma_f32_16x16x32_bf16 v[24:27], v[188:191], v[232:235], v[24:27]
	v_mfma_f32_16x16x32_bf16 v[16:19], v[196:199], v[232:235], v[16:19]
	v_mfma_f32_16x16x32_bf16 v[8:11], v[188:191], v[240:243], v[8:11]
	v_mfma_f32_16x16x32_bf16 v[0:3], v[196:199], v[240:243], v[0:3]
	s_setprio 0
	s_barrier
	s_add_i32 s85, s85, 2
	s_add_u32 s89, s89, 0x100
	s_addc_u32 s84, s84, 0
	s_add_u32 s60, s60, 0x100
	s_addc_u32 s61, s61, 0
	s_cmp_gt_u32 s85, 13
	s_cbranch_scc0 .LBB0_180
	s_and_b64 vcc, exec, s[18:19]
	s_cbranch_vccz .LBB0_183
	s_barrier

.LBB0_281:
	s_add_u32 vcc_lo, s60, 0x100
	s_addc_u32 vcc_hi, s61, 0
	s_add_i32 s87, 0, 0x10000
	s_cmp_eq_u32 s86, 40
	s_cselect_b32 s67, s51, vcc_hi
	s_cselect_b32 s66, s50, vcc_lo
	s_cselect_b32 s19, s45, s85
	s_cselect_b32 s18, s44, s84
	s_add_i32 s92, 0, 0x14000
	v_add_u32_e32 v140, s87, v210
	v_add_u32_e32 v186, s92, v210
	ds_read_b128 v[128:131], v140
	ds_read_b128 v[132:135], v140 offset:1024
	ds_read_b128 v[136:139], v140 offset:2048
	ds_read_b128 v[140:143], v140 offset:3072
	ds_read_b128 v[144:147], v186
	ds_read_b128 v[148:151], v186 offset:1024
	ds_read_b128 v[182:185], v186 offset:2048
	ds_read_b128 v[186:189], v186 offset:3072
	v_lshl_add_u64 v[198:199], s[60:61], 0, v[180:181]
	s_add_i32 m0, s69, 0xc000
	ds_read_b128 v[190:193], v212
	ds_read_b128 v[194:197], v212 offset:1024
	ds_read_b128 v[214:217], v212 offset:2048
	ds_read_b128 v[218:221], v212 offset:3072
	ds_read_b128 v[224:227], v212 offset:4096
	ds_read_b128 v[228:231], v212 offset:5120
	ds_read_b128 v[232:235], v212 offset:6144
	ds_read_b128 v[236:239], v212 offset:7168
	global_load_lds_dwordx4 v[198:199], off
	v_lshl_add_u64 v[198:199], s[60:61], 0, v[178:179]
	s_add_i32 m0, s69, 0xe000
	s_nop 0
	global_load_lds_dwordx4 v[198:199], off
	s_waitcnt vmcnt(8)
	s_waitcnt lgkmcnt(0)
	s_setprio 1
	s_barrier
	s_waitcnt lgkmcnt(0)
	v_mfma_f32_16x16x32_bf16 v[124:127], v[128:131], v[190:193], v[124:127]
	v_mfma_f32_16x16x32_bf16 v[120:123], v[136:139], v[190:193], v[120:123]
	v_mfma_f32_16x16x32_bf16 v[108:111], v[128:131], v[214:217], v[108:111]
	v_mfma_f32_16x16x32_bf16 v[104:107], v[136:139], v[214:217], v[104:107]
	v_mfma_f32_16x16x32_bf16 v[92:95], v[128:131], v[224:227], v[92:95]
	v_mfma_f32_16x16x32_bf16 v[88:91], v[136:139], v[224:227], v[88:91]
	v_mfma_f32_16x16x32_bf16 v[76:79], v[128:131], v[232:235], v[76:79]
	v_mfma_f32_16x16x32_bf16 v[72:75], v[136:139], v[232:235], v[72:75]
	v_mfma_f32_16x16x32_bf16 v[124:127], v[132:135], v[194:197], v[124:127]
	v_mfma_f32_16x16x32_bf16 v[120:123], v[140:143], v[194:197], v[120:123]
	v_mfma_f32_16x16x32_bf16 v[108:111], v[132:135], v[218:221], v[108:111]
	v_mfma_f32_16x16x32_bf16 v[104:107], v[140:143], v[218:221], v[104:107]
	v_mfma_f32_16x16x32_bf16 v[92:95], v[132:135], v[228:231], v[92:95]
	v_mfma_f32_16x16x32_bf16 v[88:91], v[140:143], v[228:231], v[88:91]
	v_mfma_f32_16x16x32_bf16 v[76:79], v[132:135], v[236:239], v[76:79]
	v_mfma_f32_16x16x32_bf16 v[72:75], v[140:143], v[236:239], v[72:75]
	s_setprio 0
	s_setprio 1
	v_mfma_f32_16x16x32_bf16 v[116:119], v[144:147], v[190:193], v[116:119]
	v_mfma_f32_16x16x32_bf16 v[112:115], v[182:185], v[190:193], v[112:115]
	v_mfma_f32_16x16x32_bf16 v[100:103], v[144:147], v[214:217], v[100:103]
	v_mfma_f32_16x16x32_bf16 v[96:99], v[182:185], v[214:217], v[96:99]
	v_mfma_f32_16x16x32_bf16 v[84:87], v[144:147], v[224:227], v[84:87]
	v_mfma_f32_16x16x32_bf16 v[80:83], v[182:185], v[224:227], v[80:83]
	v_mfma_f32_16x16x32_bf16 v[68:71], v[144:147], v[232:235], v[68:71]
	v_mfma_f32_16x16x32_bf16 v[64:67], v[182:185], v[232:235], v[64:67]
	v_mfma_f32_16x16x32_bf16 v[116:119], v[148:151], v[194:197], v[116:119]
	v_mfma_f32_16x16x32_bf16 v[112:115], v[186:189], v[194:197], v[112:115]
	v_mfma_f32_16x16x32_bf16 v[100:103], v[148:151], v[218:221], v[100:103]
	v_mfma_f32_16x16x32_bf16 v[96:99], v[186:189], v[218:221], v[96:99]
	v_mfma_f32_16x16x32_bf16 v[84:87], v[148:151], v[228:231], v[84:87]
	v_mfma_f32_16x16x32_bf16 v[80:83], v[186:189], v[228:231], v[80:83]
	v_mfma_f32_16x16x32_bf16 v[68:71], v[148:151], v[236:239], v[68:71]
	v_mfma_f32_16x16x32_bf16 v[64:67], v[186:189], v[236:239], v[64:67]
	s_setprio 0
	s_barrier
	s_add_i32 s60, s87, s68
	v_lshl_add_u64 v[198:199], s[18:19], 0, v[152:153]
	s_mov_b32 m0, s60
	ds_read_b128 v[190:193], v212 offset:16384
	ds_read_b128 v[194:197], v212 offset:17408
	ds_read_b128 v[214:217], v212 offset:18432
	ds_read_b128 v[218:221], v212 offset:19456
	ds_read_b128 v[224:227], v212 offset:20480
	ds_read_b128 v[228:231], v212 offset:21504
	ds_read_b128 v[232:235], v212 offset:22528
	ds_read_b128 v[236:239], v212 offset:23552
	global_load_lds_dwordx4 v[198:199], off
	s_add_i32 m0, s60, 0x2000
	s_add_u32 s60, s18, 0xb0000
	v_lshl_add_u64 v[240:241], s[18:19], 0, v[172:173]
	s_addc_u32 s61, s19, 0
	s_add_i32 s87, s92, s68
	global_load_lds_dwordx4 v[240:241], off
	v_lshl_add_u64 v[242:243], s[60:61], 0, v[152:153]
	s_mov_b32 m0, s87
	v_lshl_add_u64 v[244:245], s[66:67], 0, v[174:175]
	global_load_lds_dwordx4 v[242:243], off
	v_lshl_add_u64 v[242:243], s[60:61], 0, v[172:173]
	s_add_i32 m0, s87, 0x2000
	s_nop 0
	global_load_lds_dwordx4 v[242:243], off
	v_lshl_add_u64 v[242:243], s[66:67], 0, v[176:177]
	s_mov_b32 m0, s69
	s_nop 0
	global_load_lds_dwordx4 v[242:243], off
	s_mov_b32 m0, s74
	s_nop 0
	global_load_lds_dwordx4 v[244:245], off
	s_waitcnt vmcnt(8)
	s_waitcnt lgkmcnt(0)
	s_setprio 1
	s_barrier
	s_waitcnt lgkmcnt(0)
	v_mfma_f32_16x16x32_bf16 v[60:63], v[128:131], v[190:193], v[60:63]
	v_mfma_f32_16x16x32_bf16 v[56:59], v[136:139], v[190:193], v[56:59]
	v_mfma_f32_16x16x32_bf16 v[44:47], v[128:131], v[214:217], v[44:47]
	v_mfma_f32_16x16x32_bf16 v[40:43], v[136:139], v[214:217], v[40:43]
	v_mfma_f32_16x16x32_bf16 v[28:31], v[128:131], v[224:227], v[28:31]
	v_mfma_f32_16x16x32_bf16 v[24:27], v[136:139], v[224:227], v[24:27]
	v_mfma_f32_16x16x32_bf16 v[12:15], v[128:131], v[232:235], v[12:15]
	v_mfma_f32_16x16x32_bf16 v[8:11], v[136:139], v[232:235], v[8:11]
	v_mfma_f32_16x16x32_bf16 v[60:63], v[132:135], v[194:197], v[60:63]
	v_mfma_f32_16x16x32_bf16 v[56:59], v[140:143], v[194:197], v[56:59]
	v_mfma_f32_16x16x32_bf16 v[44:47], v[132:135], v[218:221], v[44:47]
	v_mfma_f32_16x16x32_bf16 v[40:43], v[140:143], v[218:221], v[40:43]
	v_mfma_f32_16x16x32_bf16 v[28:31], v[132:135], v[228:231], v[28:31]
	v_mfma_f32_16x16x32_bf16 v[24:27], v[140:143], v[228:231], v[24:27]
	v_mfma_f32_16x16x32_bf16 v[12:15], v[132:135], v[236:239], v[12:15]
	v_mfma_f32_16x16x32_bf16 v[8:11], v[140:143], v[236:239], v[8:11]
	s_setprio 0
	s_setprio 1
	v_mfma_f32_16x16x32_bf16 v[52:55], v[144:147], v[190:193], v[52:55]
	v_mfma_f32_16x16x32_bf16 v[48:51], v[182:185], v[190:193], v[48:51]
	v_mfma_f32_16x16x32_bf16 v[36:39], v[144:147], v[214:217], v[36:39]
	v_mfma_f32_16x16x32_bf16 v[32:35], v[182:185], v[214:217], v[32:35]
	v_mfma_f32_16x16x32_bf16 v[20:23], v[144:147], v[224:227], v[20:23]
	v_mfma_f32_16x16x32_bf16 v[16:19], v[182:185], v[224:227], v[16:19]
	v_mfma_f32_16x16x32_bf16 v[4:7], v[144:147], v[232:235], v[4:7]
	v_mfma_f32_16x16x32_bf16 v[0:3], v[182:185], v[232:235], v[0:3]
	v_mfma_f32_16x16x32_bf16 v[52:55], v[148:151], v[194:197], v[52:55]
	v_mfma_f32_16x16x32_bf16 v[48:51], v[186:189], v[194:197], v[48:51]
	v_mfma_f32_16x16x32_bf16 v[36:39], v[148:151], v[218:221], v[36:39]
	v_mfma_f32_16x16x32_bf16 v[32:35], v[186:189], v[218:221], v[32:35]
	v_mfma_f32_16x16x32_bf16 v[20:23], v[148:151], v[228:231], v[20:23]
	v_mfma_f32_16x16x32_bf16 v[16:19], v[186:189], v[228:231], v[16:19]
	v_mfma_f32_16x16x32_bf16 v[4:7], v[148:151], v[236:239], v[4:7]
	v_mfma_f32_16x16x32_bf16 v[0:3], v[186:189], v[236:239], v[0:3]
	s_setprio 0
	s_barrier
	s_add_i32 s87, 0, 0x18000
	s_add_i32 s92, 0, 0x1c000
	v_add_u32_e32 v140, s87, v210
	v_add_u32_e32 v186, s92, v210
	ds_read_b128 v[128:131], v140
	ds_read_b128 v[132:135], v140 offset:1024
	ds_read_b128 v[136:139], v140 offset:2048
	ds_read_b128 v[140:143], v140 offset:3072
	ds_read_b128 v[144:147], v186
	ds_read_b128 v[148:151], v186 offset:1024
	ds_read_b128 v[182:185], v186 offset:2048
	ds_read_b128 v[186:189], v186 offset:3072
	s_add_u32 s60, s66, 0xb0000
	s_addc_u32 s61, s67, 0
	s_mov_b32 m0, s75
	v_lshl_add_u64 v[246:247], s[60:61], 0, v[176:177]
	ds_read_b128 v[190:193], v212 offset:32768
	ds_read_b128 v[194:197], v212 offset:33792
	ds_read_b128 v[214:217], v212 offset:34816
	ds_read_b128 v[218:221], v212 offset:35840
	ds_read_b128 v[224:227], v212 offset:36864
	ds_read_b128 v[228:231], v212 offset:37888
	ds_read_b128 v[232:235], v212 offset:38912
	ds_read_b128 v[236:239], v212 offset:39936
	global_load_lds_dwordx4 v[246:247], off
	v_lshl_add_u64 v[246:247], s[60:61], 0, v[174:175]
	s_mov_b32 m0, s76
	s_nop 0
	global_load_lds_dwordx4 v[246:247], off
	s_waitcnt vmcnt(8)
	s_waitcnt lgkmcnt(0)
	s_setprio 1
	s_barrier
	s_waitcnt lgkmcnt(0)
	v_mfma_f32_16x16x32_bf16 v[124:127], v[128:131], v[190:193], v[124:127]
	v_mfma_f32_16x16x32_bf16 v[120:123], v[136:139], v[190:193], v[120:123]
	v_mfma_f32_16x16x32_bf16 v[108:111], v[128:131], v[214:217], v[108:111]
	v_mfma_f32_16x16x32_bf16 v[104:107], v[136:139], v[214:217], v[104:107]
	v_mfma_f32_16x16x32_bf16 v[92:95], v[128:131], v[224:227], v[92:95]
	v_mfma_f32_16x16x32_bf16 v[88:91], v[136:139], v[224:227], v[88:91]
	v_mfma_f32_16x16x32_bf16 v[76:79], v[128:131], v[232:235], v[76:79]
	v_mfma_f32_16x16x32_bf16 v[72:75], v[136:139], v[232:235], v[72:75]
	v_mfma_f32_16x16x32_bf16 v[124:127], v[132:135], v[194:197], v[124:127]
	v_mfma_f32_16x16x32_bf16 v[120:123], v[140:143], v[194:197], v[120:123]
	v_mfma_f32_16x16x32_bf16 v[108:111], v[132:135], v[218:221], v[108:111]
	v_mfma_f32_16x16x32_bf16 v[104:107], v[140:143], v[218:221], v[104:107]
	v_mfma_f32_16x16x32_bf16 v[92:95], v[132:135], v[228:231], v[92:95]
	v_mfma_f32_16x16x32_bf16 v[88:91], v[140:143], v[228:231], v[88:91]
	v_mfma_f32_16x16x32_bf16 v[76:79], v[132:135], v[236:239], v[76:79]
	v_mfma_f32_16x16x32_bf16 v[72:75], v[140:143], v[236:239], v[72:75]
	s_setprio 0
	s_setprio 1
	v_mfma_f32_16x16x32_bf16 v[116:119], v[144:147], v[190:193], v[116:119]
	v_mfma_f32_16x16x32_bf16 v[112:115], v[182:185], v[190:193], v[112:115]
	v_mfma_f32_16x16x32_bf16 v[100:103], v[144:147], v[214:217], v[100:103]
	v_mfma_f32_16x16x32_bf16 v[96:99], v[182:185], v[214:217], v[96:99]
	v_mfma_f32_16x16x32_bf16 v[84:87], v[144:147], v[224:227], v[84:87]
	v_mfma_f32_16x16x32_bf16 v[80:83], v[182:185], v[224:227], v[80:83]
	v_mfma_f32_16x16x32_bf16 v[68:71], v[144:147], v[232:235], v[68:71]
	v_mfma_f32_16x16x32_bf16 v[64:67], v[182:185], v[232:235], v[64:67]
	v_mfma_f32_16x16x32_bf16 v[116:119], v[148:151], v[194:197], v[116:119]
	v_mfma_f32_16x16x32_bf16 v[112:115], v[186:189], v[194:197], v[112:115]
	v_mfma_f32_16x16x32_bf16 v[100:103], v[148:151], v[218:221], v[100:103]
	v_mfma_f32_16x16x32_bf16 v[96:99], v[186:189], v[218:221], v[96:99]
	v_mfma_f32_16x16x32_bf16 v[84:87], v[148:151], v[228:231], v[84:87]
	v_mfma_f32_16x16x32_bf16 v[80:83], v[186:189], v[228:231], v[80:83]
	v_mfma_f32_16x16x32_bf16 v[68:71], v[148:151], v[236:239], v[68:71]
	v_mfma_f32_16x16x32_bf16 v[64:67], v[186:189], v[236:239], v[64:67]
	s_setprio 0
	s_barrier
	s_add_i32 s60, s87, s68
	v_lshl_add_u64 v[198:199], v[198:199], 0, s[22:23]
	s_mov_b32 m0, s60
	ds_read_b128 v[190:193], v212 offset:49152
	ds_read_b128 v[194:197], v212 offset:50176
	ds_read_b128 v[214:217], v212 offset:51200
	ds_read_b128 v[218:221], v212 offset:52224
	ds_read_b128 v[224:227], v212 offset:53248
	ds_read_b128 v[228:231], v212 offset:54272
	ds_read_b128 v[232:235], v212 offset:55296
	ds_read_b128 v[236:239], v212 offset:56320
	global_load_lds_dwordx4 v[198:199], off
	s_add_i32 m0, s60, 0x2000
	s_add_u32 s18, s18, 0xb0080
	v_lshl_add_u64 v[198:199], v[240:241], 0, s[22:23]
	s_addc_u32 s19, s19, 0
	s_add_i32 s60, s92, s68
	global_load_lds_dwordx4 v[198:199], off
	v_lshl_add_u64 v[198:199], s[18:19], 0, v[152:153]
	s_mov_b32 m0, s60
	s_nop 0
	global_load_lds_dwordx4 v[198:199], off
	v_lshl_add_u64 v[198:199], s[18:19], 0, v[172:173]
	s_add_i32 m0, s60, 0x2000
	s_nop 0
	global_load_lds_dwordx4 v[198:199], off
	v_lshl_add_u64 v[198:199], v[242:243], 0, s[22:23]
	s_mov_b32 m0, s79
	s_nop 0
	global_load_lds_dwordx4 v[198:199], off
	v_lshl_add_u64 v[198:199], v[244:245], 0, s[22:23]
	s_mov_b32 m0, s80
	s_nop 0
	global_load_lds_dwordx4 v[198:199], off
	s_waitcnt vmcnt(8)
	s_waitcnt lgkmcnt(0)
	s_setprio 1
	s_barrier
	s_waitcnt lgkmcnt(0)
	v_mfma_f32_16x16x32_bf16 v[60:63], v[128:131], v[190:193], v[60:63]
	v_mfma_f32_16x16x32_bf16 v[56:59], v[136:139], v[190:193], v[56:59]
	v_mfma_f32_16x16x32_bf16 v[44:47], v[128:131], v[214:217], v[44:47]
	v_mfma_f32_16x16x32_bf16 v[40:43], v[136:139], v[214:217], v[40:43]
	v_mfma_f32_16x16x32_bf16 v[28:31], v[128:131], v[224:227], v[28:31]
	v_mfma_f32_16x16x32_bf16 v[24:27], v[136:139], v[224:227], v[24:27]
	v_mfma_f32_16x16x32_bf16 v[12:15], v[128:131], v[232:235], v[12:15]
	v_mfma_f32_16x16x32_bf16 v[8:11], v[136:139], v[232:235], v[8:11]
	v_mfma_f32_16x16x32_bf16 v[60:63], v[132:135], v[194:197], v[60:63]
	v_mfma_f32_16x16x32_bf16 v[56:59], v[140:143], v[194:197], v[56:59]
	v_mfma_f32_16x16x32_bf16 v[44:47], v[132:135], v[218:221], v[44:47]
	v_mfma_f32_16x16x32_bf16 v[40:43], v[140:143], v[218:221], v[40:43]
	v_mfma_f32_16x16x32_bf16 v[28:31], v[132:135], v[228:231], v[28:31]
	v_mfma_f32_16x16x32_bf16 v[24:27], v[140:143], v[228:231], v[24:27]
	v_mfma_f32_16x16x32_bf16 v[12:15], v[132:135], v[236:239], v[12:15]
	v_mfma_f32_16x16x32_bf16 v[8:11], v[140:143], v[236:239], v[8:11]
	s_setprio 0
	s_setprio 1
	v_mfma_f32_16x16x32_bf16 v[52:55], v[144:147], v[190:193], v[52:55]
	v_mfma_f32_16x16x32_bf16 v[48:51], v[182:185], v[190:193], v[48:51]
	v_mfma_f32_16x16x32_bf16 v[36:39], v[144:147], v[214:217], v[36:39]
	v_mfma_f32_16x16x32_bf16 v[32:35], v[182:185], v[214:217], v[32:35]
	v_mfma_f32_16x16x32_bf16 v[20:23], v[144:147], v[224:227], v[20:23]
	v_mfma_f32_16x16x32_bf16 v[16:19], v[182:185], v[224:227], v[16:19]
	v_mfma_f32_16x16x32_bf16 v[4:7], v[144:147], v[232:235], v[4:7]
	v_mfma_f32_16x16x32_bf16 v[0:3], v[182:185], v[232:235], v[0:3]
	v_mfma_f32_16x16x32_bf16 v[52:55], v[148:151], v[194:197], v[52:55]
	v_mfma_f32_16x16x32_bf16 v[48:51], v[186:189], v[194:197], v[48:51]
	v_mfma_f32_16x16x32_bf16 v[36:39], v[148:151], v[218:221], v[36:39]
	v_mfma_f32_16x16x32_bf16 v[32:35], v[186:189], v[218:221], v[32:35]
	v_mfma_f32_16x16x32_bf16 v[20:23], v[148:151], v[228:231], v[20:23]
	v_mfma_f32_16x16x32_bf16 v[16:19], v[186:189], v[228:231], v[16:19]
	v_mfma_f32_16x16x32_bf16 v[4:7], v[148:151], v[236:239], v[4:7]
	v_mfma_f32_16x16x32_bf16 v[0:3], v[186:189], v[236:239], v[0:3]
	s_setprio 0
	s_barrier
	s_add_i32 s86, s86, 2
	s_add_u32 s84, s84, 0x100
	s_addc_u32 s85, s85, 0
	s_cmp_gt_u32 s86, 41
	s_mov_b64 s[60:61], vcc
	s_cbranch_scc0 .LBB0_281
	s_and_b64 vcc, exec, s[10:11]
	s_cbranch_vccz .LBB0_284
	s_barrier

.LBB0_419:
	s_add_u32 s44, s48, 0xfffc0080
	s_addc_u32 s45, s49, -1
	s_add_i32 s83, 0, 0x10000
	s_cmp_eq_u32 s82, 12
	s_cselect_b32 s63, s21, s45
	s_cselect_b32 s62, s78, s44
	s_cselect_b32 s45, s19, s81
	s_cselect_b32 s44, s79, s80
	s_add_i32 s86, 0, 0x14000
	v_add_u32_e32 v88, s83, v185
	v_add_u32_e32 v182, s86, v185
	ds_read_b128 v[72:75], v88
	ds_read_b128 v[76:79], v88 offset:1024
	ds_read_b128 v[80:83], v88 offset:2048
	ds_read_b128 v[88:91], v88 offset:3072
	ds_read_b128 v[174:177], v182
	ds_read_b128 v[178:181], v182 offset:1024
	ds_read_b128 v[190:193], v182 offset:2048
	ds_read_b128 v[194:197], v182 offset:3072
	v_lshl_add_u64 v[182:183], s[48:49], 0, v[172:173]
	s_add_i32 m0, s59, 0xc000
	ds_read_b128 v[210:213], v188
	ds_read_b128 v[214:217], v188 offset:1024
	ds_read_b128 v[218:221], v188 offset:2048
	ds_read_b128 v[224:227], v188 offset:3072
	ds_read_b128 v[228:231], v188 offset:4096
	ds_read_b128 v[232:235], v188 offset:5120
	ds_read_b128 v[236:239], v188 offset:6144
	ds_read_b128 v[240:243], v188 offset:7168
	global_load_lds_dwordx4 v[182:183], off
	v_lshl_add_u64 v[182:183], s[48:49], 0, v[150:151]
	s_add_i32 m0, s59, 0xe000
	s_nop 0
	global_load_lds_dwordx4 v[182:183], off
	s_waitcnt vmcnt(8)
	s_waitcnt lgkmcnt(0)
	s_setprio 1
	s_barrier
	s_waitcnt lgkmcnt(0)
	v_mfma_f32_16x16x32_bf16 v[140:143], v[72:75], v[210:213], v[140:143]
	v_mfma_f32_16x16x32_bf16 v[136:139], v[80:83], v[210:213], v[136:139]
	v_mfma_f32_16x16x32_bf16 v[124:127], v[72:75], v[218:221], v[124:127]
	v_mfma_f32_16x16x32_bf16 v[120:123], v[80:83], v[218:221], v[120:123]
	v_mfma_f32_16x16x32_bf16 v[108:111], v[72:75], v[228:231], v[108:111]
	v_mfma_f32_16x16x32_bf16 v[104:107], v[80:83], v[228:231], v[104:107]
	v_mfma_f32_16x16x32_bf16 v[92:95], v[72:75], v[236:239], v[92:95]
	v_mfma_f32_16x16x32_bf16 v[84:87], v[80:83], v[236:239], v[84:87]
	v_mfma_f32_16x16x32_bf16 v[140:143], v[76:79], v[214:217], v[140:143]
	v_mfma_f32_16x16x32_bf16 v[136:139], v[88:91], v[214:217], v[136:139]
	v_mfma_f32_16x16x32_bf16 v[124:127], v[76:79], v[224:227], v[124:127]
	v_mfma_f32_16x16x32_bf16 v[120:123], v[88:91], v[224:227], v[120:123]
	v_mfma_f32_16x16x32_bf16 v[108:111], v[76:79], v[232:235], v[108:111]
	v_mfma_f32_16x16x32_bf16 v[104:107], v[88:91], v[232:235], v[104:107]
	v_mfma_f32_16x16x32_bf16 v[92:95], v[76:79], v[240:243], v[92:95]
	v_mfma_f32_16x16x32_bf16 v[84:87], v[88:91], v[240:243], v[84:87]
	s_setprio 0
	s_setprio 1
	v_mfma_f32_16x16x32_bf16 v[132:135], v[174:177], v[210:213], v[132:135]
	v_mfma_f32_16x16x32_bf16 v[128:131], v[190:193], v[210:213], v[128:131]
	v_mfma_f32_16x16x32_bf16 v[116:119], v[174:177], v[218:221], v[116:119]
	v_mfma_f32_16x16x32_bf16 v[112:115], v[190:193], v[218:221], v[112:115]
	v_mfma_f32_16x16x32_bf16 v[100:103], v[174:177], v[228:231], v[100:103]
	v_mfma_f32_16x16x32_bf16 v[96:99], v[190:193], v[228:231], v[96:99]
	v_mfma_f32_16x16x32_bf16 v[68:71], v[174:177], v[236:239], v[68:71]
	v_mfma_f32_16x16x32_bf16 v[64:67], v[190:193], v[236:239], v[64:67]
	v_mfma_f32_16x16x32_bf16 v[132:135], v[178:181], v[214:217], v[132:135]
	v_mfma_f32_16x16x32_bf16 v[128:131], v[194:197], v[214:217], v[128:131]
	v_mfma_f32_16x16x32_bf16 v[116:119], v[178:181], v[224:227], v[116:119]
	v_mfma_f32_16x16x32_bf16 v[112:115], v[194:197], v[224:227], v[112:115]
	v_mfma_f32_16x16x32_bf16 v[100:103], v[178:181], v[232:235], v[100:103]
	v_mfma_f32_16x16x32_bf16 v[96:99], v[194:197], v[232:235], v[96:99]
	v_mfma_f32_16x16x32_bf16 v[68:71], v[178:181], v[240:243], v[68:71]
	v_mfma_f32_16x16x32_bf16 v[64:67], v[194:197], v[240:243], v[64:67]
	s_setprio 0
	s_barrier
	s_add_i32 s83, s83, s8
	v_lshl_add_u64 v[182:183], s[44:45], 0, v[152:153]
	s_mov_b32 m0, s83
	ds_read_b128 v[210:213], v188 offset:16384
	ds_read_b128 v[214:217], v188 offset:17408
	ds_read_b128 v[218:221], v188 offset:18432
	ds_read_b128 v[224:227], v188 offset:19456
	ds_read_b128 v[228:231], v188 offset:20480
	ds_read_b128 v[232:235], v188 offset:21504
	ds_read_b128 v[236:239], v188 offset:22528
	ds_read_b128 v[240:243], v188 offset:23552
	global_load_lds_dwordx4 v[182:183], off
	s_add_i32 m0, s83, 0x2000
	s_add_u32 s84, s44, 0x40000
	v_lshl_add_u64 v[198:199], s[44:45], 0, v[144:145]
	s_addc_u32 s85, s45, 0
	s_add_i32 s83, s86, s8
	global_load_lds_dwordx4 v[198:199], off
	v_lshl_add_u64 v[244:245], s[84:85], 0, v[152:153]
	s_mov_b32 m0, s83
	v_lshl_add_u64 v[246:247], s[62:63], 0, v[146:147]
	global_load_lds_dwordx4 v[244:245], off
	v_lshl_add_u64 v[244:245], s[84:85], 0, v[144:145]
	s_add_i32 m0, s83, 0x2000
	s_nop 0
	global_load_lds_dwordx4 v[244:245], off
	v_lshl_add_u64 v[244:245], s[62:63], 0, v[148:149]
	s_mov_b32 m0, s59
	s_nop 0
	global_load_lds_dwordx4 v[244:245], off
	s_mov_b32 m0, s66
	s_nop 0
	global_load_lds_dwordx4 v[246:247], off
	s_waitcnt vmcnt(8)
	s_waitcnt lgkmcnt(0)
	s_setprio 1
	s_barrier
	s_waitcnt lgkmcnt(0)
	v_mfma_f32_16x16x32_bf16 v[60:63], v[72:75], v[210:213], v[60:63]
	v_mfma_f32_16x16x32_bf16 v[56:59], v[80:83], v[210:213], v[56:59]
	v_mfma_f32_16x16x32_bf16 v[44:47], v[72:75], v[218:221], v[44:47]
	v_mfma_f32_16x16x32_bf16 v[40:43], v[80:83], v[218:221], v[40:43]
	v_mfma_f32_16x16x32_bf16 v[28:31], v[72:75], v[228:231], v[28:31]
	v_mfma_f32_16x16x32_bf16 v[24:27], v[80:83], v[228:231], v[24:27]
	v_mfma_f32_16x16x32_bf16 v[12:15], v[72:75], v[236:239], v[12:15]
	v_mfma_f32_16x16x32_bf16 v[8:11], v[80:83], v[236:239], v[8:11]
	v_mfma_f32_16x16x32_bf16 v[60:63], v[76:79], v[214:217], v[60:63]
	v_mfma_f32_16x16x32_bf16 v[56:59], v[88:91], v[214:217], v[56:59]
	v_mfma_f32_16x16x32_bf16 v[44:47], v[76:79], v[224:227], v[44:47]
	v_mfma_f32_16x16x32_bf16 v[40:43], v[88:91], v[224:227], v[40:43]
	v_mfma_f32_16x16x32_bf16 v[28:31], v[76:79], v[232:235], v[28:31]
	v_mfma_f32_16x16x32_bf16 v[24:27], v[88:91], v[232:235], v[24:27]
	v_mfma_f32_16x16x32_bf16 v[12:15], v[76:79], v[240:243], v[12:15]
	v_mfma_f32_16x16x32_bf16 v[8:11], v[88:91], v[240:243], v[8:11]
	s_setprio 0
	s_setprio 1
	v_mfma_f32_16x16x32_bf16 v[52:55], v[174:177], v[210:213], v[52:55]
	v_mfma_f32_16x16x32_bf16 v[48:51], v[190:193], v[210:213], v[48:51]
	v_mfma_f32_16x16x32_bf16 v[36:39], v[174:177], v[218:221], v[36:39]
	v_mfma_f32_16x16x32_bf16 v[32:35], v[190:193], v[218:221], v[32:35]
	v_mfma_f32_16x16x32_bf16 v[20:23], v[174:177], v[228:231], v[20:23]
	v_mfma_f32_16x16x32_bf16 v[16:19], v[190:193], v[228:231], v[16:19]
	v_mfma_f32_16x16x32_bf16 v[4:7], v[174:177], v[236:239], v[4:7]
	v_mfma_f32_16x16x32_bf16 v[0:3], v[190:193], v[236:239], v[0:3]
	v_mfma_f32_16x16x32_bf16 v[52:55], v[178:181], v[214:217], v[52:55]
	v_mfma_f32_16x16x32_bf16 v[48:51], v[194:197], v[214:217], v[48:51]
	v_mfma_f32_16x16x32_bf16 v[36:39], v[178:181], v[224:227], v[36:39]
	v_mfma_f32_16x16x32_bf16 v[32:35], v[194:197], v[224:227], v[32:35]
	v_mfma_f32_16x16x32_bf16 v[20:23], v[178:181], v[232:235], v[20:23]
	v_mfma_f32_16x16x32_bf16 v[16:19], v[194:197], v[232:235], v[16:19]
	v_mfma_f32_16x16x32_bf16 v[4:7], v[178:181], v[240:243], v[4:7]
	v_mfma_f32_16x16x32_bf16 v[0:3], v[194:197], v[240:243], v[0:3]
	s_setprio 0
	s_barrier
	s_add_i32 s83, 0, 0x18000
	s_add_i32 s84, 0, 0x1c000
	v_add_u32_e32 v88, s83, v185
	v_add_u32_e32 v189, s84, v185
	ds_read_b128 v[72:75], v88
	ds_read_b128 v[76:79], v88 offset:1024
	ds_read_b128 v[80:83], v88 offset:2048
	ds_read_b128 v[88:91], v88 offset:3072
	ds_read_b128 v[174:177], v189
	ds_read_b128 v[178:181], v189 offset:1024
	ds_read_b128 v[190:193], v189 offset:2048
	ds_read_b128 v[194:197], v189 offset:3072
	s_add_u32 s62, s62, 0x40000
	s_addc_u32 s63, s63, 0
	s_mov_b32 m0, s67
	v_lshl_add_u64 v[248:249], s[62:63], 0, v[148:149]
	ds_read_b128 v[210:213], v188 offset:32768
	ds_read_b128 v[214:217], v188 offset:33792
	ds_read_b128 v[218:221], v188 offset:34816
	ds_read_b128 v[224:227], v188 offset:35840
	ds_read_b128 v[228:231], v188 offset:36864
	ds_read_b128 v[232:235], v188 offset:37888
	ds_read_b128 v[236:239], v188 offset:38912
	ds_read_b128 v[240:243], v188 offset:39936
	global_load_lds_dwordx4 v[248:249], off
	v_lshl_add_u64 v[248:249], s[62:63], 0, v[146:147]
	s_mov_b32 m0, s68
	s_nop 0
	global_load_lds_dwordx4 v[248:249], off
	s_waitcnt vmcnt(8)
	s_waitcnt lgkmcnt(0)
	s_setprio 1
	s_barrier
	s_waitcnt lgkmcnt(0)
	v_mfma_f32_16x16x32_bf16 v[140:143], v[72:75], v[210:213], v[140:143]
	v_mfma_f32_16x16x32_bf16 v[136:139], v[80:83], v[210:213], v[136:139]
	v_mfma_f32_16x16x32_bf16 v[124:127], v[72:75], v[218:221], v[124:127]
	v_mfma_f32_16x16x32_bf16 v[120:123], v[80:83], v[218:221], v[120:123]
	v_mfma_f32_16x16x32_bf16 v[108:111], v[72:75], v[228:231], v[108:111]
	v_mfma_f32_16x16x32_bf16 v[104:107], v[80:83], v[228:231], v[104:107]
	v_mfma_f32_16x16x32_bf16 v[92:95], v[72:75], v[236:239], v[92:95]
	v_mfma_f32_16x16x32_bf16 v[84:87], v[80:83], v[236:239], v[84:87]
	v_mfma_f32_16x16x32_bf16 v[140:143], v[76:79], v[214:217], v[140:143]
	v_mfma_f32_16x16x32_bf16 v[136:139], v[88:91], v[214:217], v[136:139]
	v_mfma_f32_16x16x32_bf16 v[124:127], v[76:79], v[224:227], v[124:127]
	v_mfma_f32_16x16x32_bf16 v[120:123], v[88:91], v[224:227], v[120:123]
	v_mfma_f32_16x16x32_bf16 v[108:111], v[76:79], v[232:235], v[108:111]
	v_mfma_f32_16x16x32_bf16 v[104:107], v[88:91], v[232:235], v[104:107]
	v_mfma_f32_16x16x32_bf16 v[92:95], v[76:79], v[240:243], v[92:95]
	v_mfma_f32_16x16x32_bf16 v[84:87], v[88:91], v[240:243], v[84:87]
	s_setprio 0
	s_setprio 1
	v_mfma_f32_16x16x32_bf16 v[132:135], v[174:177], v[210:213], v[132:135]
	v_mfma_f32_16x16x32_bf16 v[128:131], v[190:193], v[210:213], v[128:131]
	v_mfma_f32_16x16x32_bf16 v[116:119], v[174:177], v[218:221], v[116:119]
	v_mfma_f32_16x16x32_bf16 v[112:115], v[190:193], v[218:221], v[112:115]
	v_mfma_f32_16x16x32_bf16 v[100:103], v[174:177], v[228:231], v[100:103]
	v_mfma_f32_16x16x32_bf16 v[96:99], v[190:193], v[228:231], v[96:99]
	v_mfma_f32_16x16x32_bf16 v[68:71], v[174:177], v[236:239], v[68:71]
	v_mfma_f32_16x16x32_bf16 v[64:67], v[190:193], v[236:239], v[64:67]
	v_mfma_f32_16x16x32_bf16 v[132:135], v[178:181], v[214:217], v[132:135]
	v_mfma_f32_16x16x32_bf16 v[128:131], v[194:197], v[214:217], v[128:131]
	v_mfma_f32_16x16x32_bf16 v[116:119], v[178:181], v[224:227], v[116:119]
	v_mfma_f32_16x16x32_bf16 v[112:115], v[194:197], v[224:227], v[112:115]
	v_mfma_f32_16x16x32_bf16 v[100:103], v[178:181], v[232:235], v[100:103]
	v_mfma_f32_16x16x32_bf16 v[96:99], v[194:197], v[232:235], v[96:99]
	v_mfma_f32_16x16x32_bf16 v[68:71], v[178:181], v[240:243], v[68:71]
	v_mfma_f32_16x16x32_bf16 v[64:67], v[194:197], v[240:243], v[64:67]
	s_setprio 0
	s_barrier
	s_add_i32 s62, s83, s8
	v_lshl_add_u64 v[182:183], v[182:183], 0, s[22:23]
	s_mov_b32 m0, s62
	ds_read_b128 v[210:213], v188 offset:49152
	ds_read_b128 v[214:217], v188 offset:50176
	ds_read_b128 v[218:221], v188 offset:51200
	ds_read_b128 v[224:227], v188 offset:52224
	ds_read_b128 v[228:231], v188 offset:53248
	ds_read_b128 v[232:235], v188 offset:54272
	ds_read_b128 v[236:239], v188 offset:55296
	ds_read_b128 v[240:243], v188 offset:56320
	global_load_lds_dwordx4 v[182:183], off
	s_add_i32 m0, s62, 0x2000
	s_add_u32 s44, s44, 0x40080
	v_lshl_add_u64 v[182:183], v[198:199], 0, s[22:23]
	s_addc_u32 s45, s45, 0
	s_add_i32 s62, s84, s8
	global_load_lds_dwordx4 v[182:183], off
	v_lshl_add_u64 v[182:183], s[44:45], 0, v[152:153]
	s_mov_b32 m0, s62
	s_nop 0
	global_load_lds_dwordx4 v[182:183], off
	v_lshl_add_u64 v[182:183], s[44:45], 0, v[144:145]
	s_add_i32 m0, s62, 0x2000
	s_nop 0
	global_load_lds_dwordx4 v[182:183], off
	v_lshl_add_u64 v[182:183], v[244:245], 0, s[22:23]
	s_mov_b32 m0, s69
	s_nop 0
	global_load_lds_dwordx4 v[182:183], off
	v_lshl_add_u64 v[182:183], v[246:247], 0, s[22:23]
	s_mov_b32 m0, s74
	s_nop 0
	global_load_lds_dwordx4 v[182:183], off
	s_waitcnt vmcnt(8)
	s_waitcnt lgkmcnt(0)
	s_setprio 1
	s_barrier
	s_waitcnt lgkmcnt(0)
	v_mfma_f32_16x16x32_bf16 v[60:63], v[72:75], v[210:213], v[60:63]
	v_mfma_f32_16x16x32_bf16 v[56:59], v[80:83], v[210:213], v[56:59]
	v_mfma_f32_16x16x32_bf16 v[44:47], v[72:75], v[218:221], v[44:47]
	v_mfma_f32_16x16x32_bf16 v[40:43], v[80:83], v[218:221], v[40:43]
	v_mfma_f32_16x16x32_bf16 v[28:31], v[72:75], v[228:231], v[28:31]
	v_mfma_f32_16x16x32_bf16 v[24:27], v[80:83], v[228:231], v[24:27]
	v_mfma_f32_16x16x32_bf16 v[12:15], v[72:75], v[236:239], v[12:15]
	v_mfma_f32_16x16x32_bf16 v[8:11], v[80:83], v[236:239], v[8:11]
	v_mfma_f32_16x16x32_bf16 v[60:63], v[76:79], v[214:217], v[60:63]
	v_mfma_f32_16x16x32_bf16 v[56:59], v[88:91], v[214:217], v[56:59]
	v_mfma_f32_16x16x32_bf16 v[44:47], v[76:79], v[224:227], v[44:47]
	v_mfma_f32_16x16x32_bf16 v[40:43], v[88:91], v[224:227], v[40:43]
	v_mfma_f32_16x16x32_bf16 v[28:31], v[76:79], v[232:235], v[28:31]
	v_mfma_f32_16x16x32_bf16 v[24:27], v[88:91], v[232:235], v[24:27]
	v_mfma_f32_16x16x32_bf16 v[12:15], v[76:79], v[240:243], v[12:15]
	v_mfma_f32_16x16x32_bf16 v[8:11], v[88:91], v[240:243], v[8:11]
	s_setprio 0
	s_setprio 1
	v_mfma_f32_16x16x32_bf16 v[52:55], v[174:177], v[210:213], v[52:55]
	v_mfma_f32_16x16x32_bf16 v[48:51], v[190:193], v[210:213], v[48:51]
	v_mfma_f32_16x16x32_bf16 v[36:39], v[174:177], v[218:221], v[36:39]
	v_mfma_f32_16x16x32_bf16 v[32:35], v[190:193], v[218:221], v[32:35]
	v_mfma_f32_16x16x32_bf16 v[20:23], v[174:177], v[228:231], v[20:23]
	v_mfma_f32_16x16x32_bf16 v[16:19], v[190:193], v[228:231], v[16:19]
	v_mfma_f32_16x16x32_bf16 v[4:7], v[174:177], v[236:239], v[4:7]
	v_mfma_f32_16x16x32_bf16 v[0:3], v[190:193], v[236:239], v[0:3]
	v_mfma_f32_16x16x32_bf16 v[52:55], v[178:181], v[214:217], v[52:55]
	v_mfma_f32_16x16x32_bf16 v[48:51], v[194:197], v[214:217], v[48:51]
	v_mfma_f32_16x16x32_bf16 v[36:39], v[178:181], v[224:227], v[36:39]
	v_mfma_f32_16x16x32_bf16 v[32:35], v[194:197], v[224:227], v[32:35]
	v_mfma_f32_16x16x32_bf16 v[20:23], v[178:181], v[232:235], v[20:23]
	v_mfma_f32_16x16x32_bf16 v[16:19], v[194:197], v[232:235], v[16:19]
	v_mfma_f32_16x16x32_bf16 v[4:7], v[178:181], v[240:243], v[4:7]
	v_mfma_f32_16x16x32_bf16 v[0:3], v[194:197], v[240:243], v[0:3]
	s_setprio 0
	s_barrier
	s_add_i32 s82, s82, 2
	s_add_u32 s80, s80, 0x100
	s_addc_u32 s81, s81, 0
	s_add_u32 s48, s48, 0x100
	s_addc_u32 s49, s49, 0
	s_cmp_gt_u32 s82, 13
	s_cbranch_scc0 .LBB0_419
	s_and_b64 vcc, exec, s[16:17]
	s_cbranch_vccz .LBB0_422
	s_barrier

.LBB0_705:
	s_add_u32 s44, s60, 0xfffe0080
	s_addc_u32 s45, s61, -1
	s_add_i32 s83, 0, 0x10000
	s_cmp_eq_u32 s82, 4
	s_cselect_b32 s63, s21, s45
	s_cselect_b32 s62, s78, s44
	s_cselect_b32 s45, s19, s81
	s_cselect_b32 s44, s79, s80
	s_add_i32 s86, 0, 0x14000
	v_add_u32_e32 v140, s83, v195
	v_add_u32_e32 v186, s86, v195
	ds_read_b128 v[124:127], v140
	ds_read_b128 v[132:135], v140 offset:1024
	ds_read_b128 v[136:139], v140 offset:2048
	ds_read_b128 v[140:143], v140 offset:3072
	ds_read_b128 v[144:147], v186
	ds_read_b128 v[148:151], v186 offset:1024
	ds_read_b128 v[182:185], v186 offset:2048
	ds_read_b128 v[186:189], v186 offset:3072
	v_lshl_add_u64 v[198:199], s[60:61], 0, v[180:181]
	s_add_i32 m0, s59, 0xc000
	ds_read_b128 v[190:193], v197
	ds_read_b128 v[210:213], v197 offset:1024
	ds_read_b128 v[214:217], v197 offset:2048
	ds_read_b128 v[218:221], v197 offset:3072
	ds_read_b128 v[224:227], v197 offset:4096
	ds_read_b128 v[228:231], v197 offset:5120
	ds_read_b128 v[232:235], v197 offset:6144
	ds_read_b128 v[236:239], v197 offset:7168
	global_load_lds_dwordx4 v[198:199], off
	v_lshl_add_u64 v[198:199], s[60:61], 0, v[178:179]
	s_add_i32 m0, s59, 0xe000
	s_nop 0
	global_load_lds_dwordx4 v[198:199], off
	s_waitcnt vmcnt(8)
	s_waitcnt lgkmcnt(0)
	s_setprio 1
	s_barrier
	s_waitcnt lgkmcnt(0)
	v_mfma_f32_16x16x32_bf16 v[128:131], v[124:127], v[190:193], v[128:131]
	v_mfma_f32_16x16x32_bf16 v[120:123], v[136:139], v[190:193], v[120:123]
	v_mfma_f32_16x16x32_bf16 v[108:111], v[124:127], v[214:217], v[108:111]
	v_mfma_f32_16x16x32_bf16 v[104:107], v[136:139], v[214:217], v[104:107]
	v_mfma_f32_16x16x32_bf16 v[92:95], v[124:127], v[224:227], v[92:95]
	v_mfma_f32_16x16x32_bf16 v[88:91], v[136:139], v[224:227], v[88:91]
	v_mfma_f32_16x16x32_bf16 v[76:79], v[124:127], v[232:235], v[76:79]
	v_mfma_f32_16x16x32_bf16 v[72:75], v[136:139], v[232:235], v[72:75]
	v_mfma_f32_16x16x32_bf16 v[128:131], v[132:135], v[210:213], v[128:131]
	v_mfma_f32_16x16x32_bf16 v[120:123], v[140:143], v[210:213], v[120:123]
	v_mfma_f32_16x16x32_bf16 v[108:111], v[132:135], v[218:221], v[108:111]
	v_mfma_f32_16x16x32_bf16 v[104:107], v[140:143], v[218:221], v[104:107]
	v_mfma_f32_16x16x32_bf16 v[92:95], v[132:135], v[228:231], v[92:95]
	v_mfma_f32_16x16x32_bf16 v[88:91], v[140:143], v[228:231], v[88:91]
	v_mfma_f32_16x16x32_bf16 v[76:79], v[132:135], v[236:239], v[76:79]
	v_mfma_f32_16x16x32_bf16 v[72:75], v[140:143], v[236:239], v[72:75]
	s_setprio 0
	s_setprio 1
	v_mfma_f32_16x16x32_bf16 v[116:119], v[144:147], v[190:193], v[116:119]
	v_mfma_f32_16x16x32_bf16 v[112:115], v[182:185], v[190:193], v[112:115]
	v_mfma_f32_16x16x32_bf16 v[100:103], v[144:147], v[214:217], v[100:103]
	v_mfma_f32_16x16x32_bf16 v[96:99], v[182:185], v[214:217], v[96:99]
	v_mfma_f32_16x16x32_bf16 v[84:87], v[144:147], v[224:227], v[84:87]
	v_mfma_f32_16x16x32_bf16 v[80:83], v[182:185], v[224:227], v[80:83]
	v_mfma_f32_16x16x32_bf16 v[68:71], v[144:147], v[232:235], v[68:71]
	v_mfma_f32_16x16x32_bf16 v[64:67], v[182:185], v[232:235], v[64:67]
	v_mfma_f32_16x16x32_bf16 v[116:119], v[148:151], v[210:213], v[116:119]
	v_mfma_f32_16x16x32_bf16 v[112:115], v[186:189], v[210:213], v[112:115]
	v_mfma_f32_16x16x32_bf16 v[100:103], v[148:151], v[218:221], v[100:103]
	v_mfma_f32_16x16x32_bf16 v[96:99], v[186:189], v[218:221], v[96:99]
	v_mfma_f32_16x16x32_bf16 v[84:87], v[148:151], v[228:231], v[84:87]
	v_mfma_f32_16x16x32_bf16 v[80:83], v[186:189], v[228:231], v[80:83]
	v_mfma_f32_16x16x32_bf16 v[68:71], v[148:151], v[236:239], v[68:71]
	v_mfma_f32_16x16x32_bf16 v[64:67], v[186:189], v[236:239], v[64:67]
	s_setprio 0
	s_barrier
	s_add_i32 s83, s83, s8
	v_lshl_add_u64 v[198:199], s[44:45], 0, v[152:153]
	s_mov_b32 m0, s83
	ds_read_b128 v[190:193], v197 offset:16384
	ds_read_b128 v[210:213], v197 offset:17408
	ds_read_b128 v[214:217], v197 offset:18432
	ds_read_b128 v[218:221], v197 offset:19456
	ds_read_b128 v[224:227], v197 offset:20480
	ds_read_b128 v[228:231], v197 offset:21504
	ds_read_b128 v[232:235], v197 offset:22528
	ds_read_b128 v[236:239], v197 offset:23552
	global_load_lds_dwordx4 v[198:199], off
	s_add_i32 m0, s83, 0x2000
	s_add_u32 s84, s44, 0x20000
	v_lshl_add_u64 v[240:241], s[44:45], 0, v[172:173]
	s_addc_u32 s85, s45, 0
	s_add_i32 s83, s86, s8
	global_load_lds_dwordx4 v[240:241], off
	v_lshl_add_u64 v[242:243], s[84:85], 0, v[152:153]
	s_mov_b32 m0, s83
	v_lshl_add_u64 v[244:245], s[62:63], 0, v[174:175]
	global_load_lds_dwordx4 v[242:243], off
	v_lshl_add_u64 v[242:243], s[84:85], 0, v[172:173]
	s_add_i32 m0, s83, 0x2000
	s_nop 0
	global_load_lds_dwordx4 v[242:243], off
	v_lshl_add_u64 v[242:243], s[62:63], 0, v[176:177]
	s_mov_b32 m0, s59
	s_nop 0
	global_load_lds_dwordx4 v[242:243], off
	s_mov_b32 m0, s66
	s_nop 0
	global_load_lds_dwordx4 v[244:245], off
	s_waitcnt vmcnt(8)
	s_waitcnt lgkmcnt(0)
	s_setprio 1
	s_barrier
	s_waitcnt lgkmcnt(0)
	v_mfma_f32_16x16x32_bf16 v[60:63], v[124:127], v[190:193], v[60:63]
	v_mfma_f32_16x16x32_bf16 v[56:59], v[136:139], v[190:193], v[56:59]
	v_mfma_f32_16x16x32_bf16 v[48:51], v[124:127], v[214:217], v[48:51]
	v_mfma_f32_16x16x32_bf16 v[40:43], v[136:139], v[214:217], v[40:43]
	v_mfma_f32_16x16x32_bf16 v[32:35], v[124:127], v[224:227], v[32:35]
	v_mfma_f32_16x16x32_bf16 v[24:27], v[136:139], v[224:227], v[24:27]
	v_mfma_f32_16x16x32_bf16 v[16:19], v[124:127], v[232:235], v[16:19]
	v_mfma_f32_16x16x32_bf16 v[8:11], v[136:139], v[232:235], v[8:11]
	v_mfma_f32_16x16x32_bf16 v[60:63], v[132:135], v[210:213], v[60:63]
	v_mfma_f32_16x16x32_bf16 v[56:59], v[140:143], v[210:213], v[56:59]
	v_mfma_f32_16x16x32_bf16 v[48:51], v[132:135], v[218:221], v[48:51]
	v_mfma_f32_16x16x32_bf16 v[40:43], v[140:143], v[218:221], v[40:43]
	v_mfma_f32_16x16x32_bf16 v[32:35], v[132:135], v[228:231], v[32:35]
	v_mfma_f32_16x16x32_bf16 v[24:27], v[140:143], v[228:231], v[24:27]
	v_mfma_f32_16x16x32_bf16 v[16:19], v[132:135], v[236:239], v[16:19]
	v_mfma_f32_16x16x32_bf16 v[8:11], v[140:143], v[236:239], v[8:11]
	s_setprio 0
	s_setprio 1
	v_mfma_f32_16x16x32_bf16 v[52:55], v[144:147], v[190:193], v[52:55]
	v_mfma_f32_16x16x32_bf16 v[44:47], v[182:185], v[190:193], v[44:47]
	v_mfma_f32_16x16x32_bf16 v[36:39], v[144:147], v[214:217], v[36:39]
	v_mfma_f32_16x16x32_bf16 v[28:31], v[182:185], v[214:217], v[28:31]
	v_mfma_f32_16x16x32_bf16 v[20:23], v[144:147], v[224:227], v[20:23]
	v_mfma_f32_16x16x32_bf16 v[12:15], v[182:185], v[224:227], v[12:15]
	v_mfma_f32_16x16x32_bf16 v[4:7], v[144:147], v[232:235], v[4:7]
	v_mfma_f32_16x16x32_bf16 v[0:3], v[182:185], v[232:235], v[0:3]
	v_mfma_f32_16x16x32_bf16 v[52:55], v[148:151], v[210:213], v[52:55]
	v_mfma_f32_16x16x32_bf16 v[44:47], v[186:189], v[210:213], v[44:47]
	v_mfma_f32_16x16x32_bf16 v[36:39], v[148:151], v[218:221], v[36:39]
	v_mfma_f32_16x16x32_bf16 v[28:31], v[186:189], v[218:221], v[28:31]
	v_mfma_f32_16x16x32_bf16 v[20:23], v[148:151], v[228:231], v[20:23]
	v_mfma_f32_16x16x32_bf16 v[12:15], v[186:189], v[228:231], v[12:15]
	v_mfma_f32_16x16x32_bf16 v[4:7], v[148:151], v[236:239], v[4:7]
	v_mfma_f32_16x16x32_bf16 v[0:3], v[186:189], v[236:239], v[0:3]
	s_setprio 0
	s_barrier
	s_add_i32 s83, 0, 0x18000
	s_add_i32 s84, 0, 0x1c000
	v_add_u32_e32 v140, s83, v195
	v_add_u32_e32 v186, s84, v195
	ds_read_b128 v[124:127], v140
	ds_read_b128 v[132:135], v140 offset:1024
	ds_read_b128 v[136:139], v140 offset:2048
	ds_read_b128 v[140:143], v140 offset:3072
	ds_read_b128 v[144:147], v186
	ds_read_b128 v[148:151], v186 offset:1024
	ds_read_b128 v[182:185], v186 offset:2048
	ds_read_b128 v[186:189], v186 offset:3072
	s_add_u32 s62, s62, 0x20000
	s_addc_u32 s63, s63, 0
	s_mov_b32 m0, s67
	v_lshl_add_u64 v[246:247], s[62:63], 0, v[176:177]
	ds_read_b128 v[190:193], v197 offset:32768
	ds_read_b128 v[210:213], v197 offset:33792
	ds_read_b128 v[214:217], v197 offset:34816
	ds_read_b128 v[218:221], v197 offset:35840
	ds_read_b128 v[224:227], v197 offset:36864
	ds_read_b128 v[228:231], v197 offset:37888
	ds_read_b128 v[232:235], v197 offset:38912
	ds_read_b128 v[236:239], v197 offset:39936
	global_load_lds_dwordx4 v[246:247], off
	v_lshl_add_u64 v[246:247], s[62:63], 0, v[174:175]
	s_mov_b32 m0, s68
	s_nop 0
	global_load_lds_dwordx4 v[246:247], off
	s_waitcnt vmcnt(8)
	s_waitcnt lgkmcnt(0)
	s_setprio 1
	s_barrier
	s_waitcnt lgkmcnt(0)
	v_mfma_f32_16x16x32_bf16 v[128:131], v[124:127], v[190:193], v[128:131]
	v_mfma_f32_16x16x32_bf16 v[120:123], v[136:139], v[190:193], v[120:123]
	v_mfma_f32_16x16x32_bf16 v[108:111], v[124:127], v[214:217], v[108:111]
	v_mfma_f32_16x16x32_bf16 v[104:107], v[136:139], v[214:217], v[104:107]
	v_mfma_f32_16x16x32_bf16 v[92:95], v[124:127], v[224:227], v[92:95]
	v_mfma_f32_16x16x32_bf16 v[88:91], v[136:139], v[224:227], v[88:91]
	v_mfma_f32_16x16x32_bf16 v[76:79], v[124:127], v[232:235], v[76:79]
	v_mfma_f32_16x16x32_bf16 v[72:75], v[136:139], v[232:235], v[72:75]
	v_mfma_f32_16x16x32_bf16 v[128:131], v[132:135], v[210:213], v[128:131]
	v_mfma_f32_16x16x32_bf16 v[120:123], v[140:143], v[210:213], v[120:123]
	v_mfma_f32_16x16x32_bf16 v[108:111], v[132:135], v[218:221], v[108:111]
	v_mfma_f32_16x16x32_bf16 v[104:107], v[140:143], v[218:221], v[104:107]
	v_mfma_f32_16x16x32_bf16 v[92:95], v[132:135], v[228:231], v[92:95]
	v_mfma_f32_16x16x32_bf16 v[88:91], v[140:143], v[228:231], v[88:91]
	v_mfma_f32_16x16x32_bf16 v[76:79], v[132:135], v[236:239], v[76:79]
	v_mfma_f32_16x16x32_bf16 v[72:75], v[140:143], v[236:239], v[72:75]
	s_setprio 0
	s_setprio 1
	v_mfma_f32_16x16x32_bf16 v[116:119], v[144:147], v[190:193], v[116:119]
	v_mfma_f32_16x16x32_bf16 v[112:115], v[182:185], v[190:193], v[112:115]
	v_mfma_f32_16x16x32_bf16 v[100:103], v[144:147], v[214:217], v[100:103]
	v_mfma_f32_16x16x32_bf16 v[96:99], v[182:185], v[214:217], v[96:99]
	v_mfma_f32_16x16x32_bf16 v[84:87], v[144:147], v[224:227], v[84:87]
	v_mfma_f32_16x16x32_bf16 v[80:83], v[182:185], v[224:227], v[80:83]
	v_mfma_f32_16x16x32_bf16 v[68:71], v[144:147], v[232:235], v[68:71]
	v_mfma_f32_16x16x32_bf16 v[64:67], v[182:185], v[232:235], v[64:67]
	v_mfma_f32_16x16x32_bf16 v[116:119], v[148:151], v[210:213], v[116:119]
	v_mfma_f32_16x16x32_bf16 v[112:115], v[186:189], v[210:213], v[112:115]
	v_mfma_f32_16x16x32_bf16 v[100:103], v[148:151], v[218:221], v[100:103]
	v_mfma_f32_16x16x32_bf16 v[96:99], v[186:189], v[218:221], v[96:99]
	v_mfma_f32_16x16x32_bf16 v[84:87], v[148:151], v[228:231], v[84:87]
	v_mfma_f32_16x16x32_bf16 v[80:83], v[186:189], v[228:231], v[80:83]
	v_mfma_f32_16x16x32_bf16 v[68:71], v[148:151], v[236:239], v[68:71]
	v_mfma_f32_16x16x32_bf16 v[64:67], v[186:189], v[236:239], v[64:67]
	s_setprio 0
	s_barrier
	s_add_i32 s62, s83, s8
	v_lshl_add_u64 v[198:199], v[198:199], 0, s[22:23]
	s_mov_b32 m0, s62
	ds_read_b128 v[190:193], v197 offset:49152
	ds_read_b128 v[210:213], v197 offset:50176
	ds_read_b128 v[214:217], v197 offset:51200
	ds_read_b128 v[218:221], v197 offset:52224
	ds_read_b128 v[224:227], v197 offset:53248
	ds_read_b128 v[228:231], v197 offset:54272
	ds_read_b128 v[232:235], v197 offset:55296
	ds_read_b128 v[236:239], v197 offset:56320
	global_load_lds_dwordx4 v[198:199], off
	s_add_i32 m0, s62, 0x2000
	s_add_u32 s44, s44, 0x20080
	v_lshl_add_u64 v[198:199], v[240:241], 0, s[22:23]
	s_addc_u32 s45, s45, 0
	s_add_i32 s62, s84, s8
	global_load_lds_dwordx4 v[198:199], off
	v_lshl_add_u64 v[198:199], s[44:45], 0, v[152:153]
	s_mov_b32 m0, s62
	s_nop 0
	global_load_lds_dwordx4 v[198:199], off
	v_lshl_add_u64 v[198:199], s[44:45], 0, v[172:173]
	s_add_i32 m0, s62, 0x2000
	s_nop 0
	global_load_lds_dwordx4 v[198:199], off
	v_lshl_add_u64 v[198:199], v[242:243], 0, s[22:23]
	s_mov_b32 m0, s69
	s_nop 0
	global_load_lds_dwordx4 v[198:199], off
	v_lshl_add_u64 v[198:199], v[244:245], 0, s[22:23]
	s_mov_b32 m0, s74
	s_nop 0
	global_load_lds_dwordx4 v[198:199], off
	s_waitcnt vmcnt(8)
	s_waitcnt lgkmcnt(0)
	s_setprio 1
	s_barrier
	s_waitcnt lgkmcnt(0)
	v_mfma_f32_16x16x32_bf16 v[60:63], v[124:127], v[190:193], v[60:63]
	v_mfma_f32_16x16x32_bf16 v[56:59], v[136:139], v[190:193], v[56:59]
	v_mfma_f32_16x16x32_bf16 v[48:51], v[124:127], v[214:217], v[48:51]
	v_mfma_f32_16x16x32_bf16 v[40:43], v[136:139], v[214:217], v[40:43]
	v_mfma_f32_16x16x32_bf16 v[32:35], v[124:127], v[224:227], v[32:35]
	v_mfma_f32_16x16x32_bf16 v[24:27], v[136:139], v[224:227], v[24:27]
	v_mfma_f32_16x16x32_bf16 v[16:19], v[124:127], v[232:235], v[16:19]
	v_mfma_f32_16x16x32_bf16 v[8:11], v[136:139], v[232:235], v[8:11]
	v_mfma_f32_16x16x32_bf16 v[60:63], v[132:135], v[210:213], v[60:63]
	v_mfma_f32_16x16x32_bf16 v[56:59], v[140:143], v[210:213], v[56:59]
	v_mfma_f32_16x16x32_bf16 v[48:51], v[132:135], v[218:221], v[48:51]
	v_mfma_f32_16x16x32_bf16 v[40:43], v[140:143], v[218:221], v[40:43]
	v_mfma_f32_16x16x32_bf16 v[32:35], v[132:135], v[228:231], v[32:35]
	v_mfma_f32_16x16x32_bf16 v[24:27], v[140:143], v[228:231], v[24:27]
	v_mfma_f32_16x16x32_bf16 v[16:19], v[132:135], v[236:239], v[16:19]
	v_mfma_f32_16x16x32_bf16 v[8:11], v[140:143], v[236:239], v[8:11]
	s_setprio 0
	s_setprio 1
	v_mfma_f32_16x16x32_bf16 v[52:55], v[144:147], v[190:193], v[52:55]
	v_mfma_f32_16x16x32_bf16 v[44:47], v[182:185], v[190:193], v[44:47]
	v_mfma_f32_16x16x32_bf16 v[36:39], v[144:147], v[214:217], v[36:39]
	v_mfma_f32_16x16x32_bf16 v[28:31], v[182:185], v[214:217], v[28:31]
	v_mfma_f32_16x16x32_bf16 v[20:23], v[144:147], v[224:227], v[20:23]
	v_mfma_f32_16x16x32_bf16 v[12:15], v[182:185], v[224:227], v[12:15]
	v_mfma_f32_16x16x32_bf16 v[4:7], v[144:147], v[232:235], v[4:7]
	v_mfma_f32_16x16x32_bf16 v[0:3], v[182:185], v[232:235], v[0:3]
	v_mfma_f32_16x16x32_bf16 v[52:55], v[148:151], v[210:213], v[52:55]
	v_mfma_f32_16x16x32_bf16 v[44:47], v[186:189], v[210:213], v[44:47]
	v_mfma_f32_16x16x32_bf16 v[36:39], v[148:151], v[218:221], v[36:39]
	v_mfma_f32_16x16x32_bf16 v[28:31], v[186:189], v[218:221], v[28:31]
	v_mfma_f32_16x16x32_bf16 v[20:23], v[148:151], v[228:231], v[20:23]
	v_mfma_f32_16x16x32_bf16 v[12:15], v[186:189], v[228:231], v[12:15]
	v_mfma_f32_16x16x32_bf16 v[4:7], v[148:151], v[236:239], v[4:7]
	v_mfma_f32_16x16x32_bf16 v[0:3], v[186:189], v[236:239], v[0:3]
	s_setprio 0
	s_barrier
	s_add_i32 s82, s82, 2
	s_add_u32 s80, s80, 0x100
	s_addc_u32 s81, s81, 0
	s_add_u32 s60, s60, 0x100
	s_addc_u32 s61, s61, 0
	s_cmp_gt_u32 s82, 5
	s_cbranch_scc0 .LBB0_705
	s_and_b64 vcc, exec, s[16:17]
	s_cbranch_vccz .LBB0_708
	s_barrier

.LBB0_725:
	s_add_u32 s44, s60, 0xfffe0080
	s_addc_u32 s45, s61, -1
	s_add_i32 s83, 0, 0x10000
	s_cmp_eq_u32 s82, 4
	s_cselect_b32 s63, s21, s45
	s_cselect_b32 s62, s78, s44
	s_cselect_b32 s45, s19, s81
	s_cselect_b32 s44, s79, s80
	s_add_i32 s86, 0, 0x14000
	v_add_u32_e32 v140, s83, v181
	v_add_u32_e32 v178, s86, v181
	ds_read_b128 v[128:131], v140
	ds_read_b128 v[132:135], v140 offset:1024
	ds_read_b128 v[136:139], v140 offset:2048
	ds_read_b128 v[140:143], v140 offset:3072
	ds_read_b128 v[174:177], v178
	ds_read_b128 v[184:187], v178 offset:1024
	ds_read_b128 v[188:191], v178 offset:2048
	ds_read_b128 v[192:195], v178 offset:3072
	v_lshl_add_u64 v[178:179], s[60:61], 0, v[172:173]
	s_add_i32 m0, s59, 0xc000
	ds_read_b128 v[196:199], v183
	ds_read_b128 v[210:213], v183 offset:1024
	ds_read_b128 v[214:217], v183 offset:2048
	ds_read_b128 v[218:221], v183 offset:3072
	ds_read_b128 v[224:227], v183 offset:4096
	ds_read_b128 v[228:231], v183 offset:5120
	ds_read_b128 v[232:235], v183 offset:6144
	ds_read_b128 v[236:239], v183 offset:7168
	global_load_lds_dwordx4 v[178:179], off
	v_lshl_add_u64 v[178:179], s[60:61], 0, v[150:151]
	s_add_i32 m0, s59, 0xe000
	s_nop 0
	global_load_lds_dwordx4 v[178:179], off
	s_waitcnt vmcnt(8)
	s_waitcnt lgkmcnt(0)
	s_setprio 1
	s_barrier
	s_waitcnt lgkmcnt(0)
	v_mfma_f32_16x16x32_bf16 v[124:127], v[128:131], v[196:199], v[124:127]
	v_mfma_f32_16x16x32_bf16 v[120:123], v[136:139], v[196:199], v[120:123]
	v_mfma_f32_16x16x32_bf16 v[108:111], v[128:131], v[214:217], v[108:111]
	v_mfma_f32_16x16x32_bf16 v[104:107], v[136:139], v[214:217], v[104:107]
	v_mfma_f32_16x16x32_bf16 v[92:95], v[128:131], v[224:227], v[92:95]
	v_mfma_f32_16x16x32_bf16 v[88:91], v[136:139], v[224:227], v[88:91]
	v_mfma_f32_16x16x32_bf16 v[76:79], v[128:131], v[232:235], v[76:79]
	v_mfma_f32_16x16x32_bf16 v[72:75], v[136:139], v[232:235], v[72:75]
	v_mfma_f32_16x16x32_bf16 v[124:127], v[132:135], v[210:213], v[124:127]
	v_mfma_f32_16x16x32_bf16 v[120:123], v[140:143], v[210:213], v[120:123]
	v_mfma_f32_16x16x32_bf16 v[108:111], v[132:135], v[218:221], v[108:111]
	v_mfma_f32_16x16x32_bf16 v[104:107], v[140:143], v[218:221], v[104:107]
	v_mfma_f32_16x16x32_bf16 v[92:95], v[132:135], v[228:231], v[92:95]
	v_mfma_f32_16x16x32_bf16 v[88:91], v[140:143], v[228:231], v[88:91]
	v_mfma_f32_16x16x32_bf16 v[76:79], v[132:135], v[236:239], v[76:79]
	v_mfma_f32_16x16x32_bf16 v[72:75], v[140:143], v[236:239], v[72:75]
	s_setprio 0
	s_setprio 1
	v_mfma_f32_16x16x32_bf16 v[116:119], v[174:177], v[196:199], v[116:119]
	v_mfma_f32_16x16x32_bf16 v[112:115], v[188:191], v[196:199], v[112:115]
	v_mfma_f32_16x16x32_bf16 v[100:103], v[174:177], v[214:217], v[100:103]
	v_mfma_f32_16x16x32_bf16 v[96:99], v[188:191], v[214:217], v[96:99]
	v_mfma_f32_16x16x32_bf16 v[84:87], v[174:177], v[224:227], v[84:87]
	v_mfma_f32_16x16x32_bf16 v[80:83], v[188:191], v[224:227], v[80:83]
	v_mfma_f32_16x16x32_bf16 v[68:71], v[174:177], v[232:235], v[68:71]
	v_mfma_f32_16x16x32_bf16 v[64:67], v[188:191], v[232:235], v[64:67]
	v_mfma_f32_16x16x32_bf16 v[116:119], v[184:187], v[210:213], v[116:119]
	v_mfma_f32_16x16x32_bf16 v[112:115], v[192:195], v[210:213], v[112:115]
	v_mfma_f32_16x16x32_bf16 v[100:103], v[184:187], v[218:221], v[100:103]
	v_mfma_f32_16x16x32_bf16 v[96:99], v[192:195], v[218:221], v[96:99]
	v_mfma_f32_16x16x32_bf16 v[84:87], v[184:187], v[228:231], v[84:87]
	v_mfma_f32_16x16x32_bf16 v[80:83], v[192:195], v[228:231], v[80:83]
	v_mfma_f32_16x16x32_bf16 v[68:71], v[184:187], v[236:239], v[68:71]
	v_mfma_f32_16x16x32_bf16 v[64:67], v[192:195], v[236:239], v[64:67]
	s_setprio 0
	s_barrier
	s_add_i32 s83, s83, s8
	v_lshl_add_u64 v[178:179], s[44:45], 0, v[152:153]
	s_mov_b32 m0, s83
	ds_read_b128 v[196:199], v183 offset:16384
	ds_read_b128 v[210:213], v183 offset:17408
	ds_read_b128 v[214:217], v183 offset:18432
	ds_read_b128 v[218:221], v183 offset:19456
	ds_read_b128 v[224:227], v183 offset:20480
	ds_read_b128 v[228:231], v183 offset:21504
	ds_read_b128 v[232:235], v183 offset:22528
	ds_read_b128 v[236:239], v183 offset:23552
	global_load_lds_dwordx4 v[178:179], off
	s_add_i32 m0, s83, 0x2000
	s_add_u32 s84, s44, 0x20000
	v_lshl_add_u64 v[240:241], s[44:45], 0, v[144:145]
	s_addc_u32 s85, s45, 0
	s_add_i32 s83, s86, s8
	global_load_lds_dwordx4 v[240:241], off
	v_lshl_add_u64 v[242:243], s[84:85], 0, v[152:153]
	s_mov_b32 m0, s83
	v_lshl_add_u64 v[244:245], s[62:63], 0, v[146:147]
	global_load_lds_dwordx4 v[242:243], off
	v_lshl_add_u64 v[242:243], s[84:85], 0, v[144:145]
	s_add_i32 m0, s83, 0x2000
	s_nop 0
	global_load_lds_dwordx4 v[242:243], off
	v_lshl_add_u64 v[242:243], s[62:63], 0, v[148:149]
	s_mov_b32 m0, s59
	s_nop 0
	global_load_lds_dwordx4 v[242:243], off
	s_mov_b32 m0, s66
	s_nop 0
	global_load_lds_dwordx4 v[244:245], off
	s_waitcnt vmcnt(8)
	s_waitcnt lgkmcnt(0)
	s_setprio 1
	s_barrier
	s_waitcnt lgkmcnt(0)
	v_mfma_f32_16x16x32_bf16 v[60:63], v[128:131], v[196:199], v[60:63]
	v_mfma_f32_16x16x32_bf16 v[56:59], v[136:139], v[196:199], v[56:59]
	v_mfma_f32_16x16x32_bf16 v[44:47], v[128:131], v[214:217], v[44:47]
	v_mfma_f32_16x16x32_bf16 v[40:43], v[136:139], v[214:217], v[40:43]
	v_mfma_f32_16x16x32_bf16 v[28:31], v[128:131], v[224:227], v[28:31]
	v_mfma_f32_16x16x32_bf16 v[24:27], v[136:139], v[224:227], v[24:27]
	v_mfma_f32_16x16x32_bf16 v[12:15], v[128:131], v[232:235], v[12:15]
	v_mfma_f32_16x16x32_bf16 v[8:11], v[136:139], v[232:235], v[8:11]
	v_mfma_f32_16x16x32_bf16 v[60:63], v[132:135], v[210:213], v[60:63]
	v_mfma_f32_16x16x32_bf16 v[56:59], v[140:143], v[210:213], v[56:59]
	v_mfma_f32_16x16x32_bf16 v[44:47], v[132:135], v[218:221], v[44:47]
	v_mfma_f32_16x16x32_bf16 v[40:43], v[140:143], v[218:221], v[40:43]
	v_mfma_f32_16x16x32_bf16 v[28:31], v[132:135], v[228:231], v[28:31]
	v_mfma_f32_16x16x32_bf16 v[24:27], v[140:143], v[228:231], v[24:27]
	v_mfma_f32_16x16x32_bf16 v[12:15], v[132:135], v[236:239], v[12:15]
	v_mfma_f32_16x16x32_bf16 v[8:11], v[140:143], v[236:239], v[8:11]
	s_setprio 0
	s_setprio 1
	v_mfma_f32_16x16x32_bf16 v[52:55], v[174:177], v[196:199], v[52:55]
	v_mfma_f32_16x16x32_bf16 v[48:51], v[188:191], v[196:199], v[48:51]
	v_mfma_f32_16x16x32_bf16 v[36:39], v[174:177], v[214:217], v[36:39]
	v_mfma_f32_16x16x32_bf16 v[32:35], v[188:191], v[214:217], v[32:35]
	v_mfma_f32_16x16x32_bf16 v[20:23], v[174:177], v[224:227], v[20:23]
	v_mfma_f32_16x16x32_bf16 v[16:19], v[188:191], v[224:227], v[16:19]
	v_mfma_f32_16x16x32_bf16 v[4:7], v[174:177], v[232:235], v[4:7]
	v_mfma_f32_16x16x32_bf16 v[0:3], v[188:191], v[232:235], v[0:3]
	v_mfma_f32_16x16x32_bf16 v[52:55], v[184:187], v[210:213], v[52:55]
	v_mfma_f32_16x16x32_bf16 v[48:51], v[192:195], v[210:213], v[48:51]
	v_mfma_f32_16x16x32_bf16 v[36:39], v[184:187], v[218:221], v[36:39]
	v_mfma_f32_16x16x32_bf16 v[32:35], v[192:195], v[218:221], v[32:35]
	v_mfma_f32_16x16x32_bf16 v[20:23], v[184:187], v[228:231], v[20:23]
	v_mfma_f32_16x16x32_bf16 v[16:19], v[192:195], v[228:231], v[16:19]
	v_mfma_f32_16x16x32_bf16 v[4:7], v[184:187], v[236:239], v[4:7]
	v_mfma_f32_16x16x32_bf16 v[0:3], v[192:195], v[236:239], v[0:3]
	s_setprio 0
	s_barrier
	s_add_i32 s83, 0, 0x18000
	s_add_i32 s84, 0, 0x1c000
	v_add_u32_e32 v140, s83, v181
	v_add_u32_e32 v192, s84, v181
	ds_read_b128 v[128:131], v140
	ds_read_b128 v[132:135], v140 offset:1024
	ds_read_b128 v[136:139], v140 offset:2048
	ds_read_b128 v[140:143], v140 offset:3072
	ds_read_b128 v[174:177], v192
	ds_read_b128 v[184:187], v192 offset:1024
	ds_read_b128 v[188:191], v192 offset:2048
	ds_read_b128 v[192:195], v192 offset:3072
	s_add_u32 s62, s62, 0x20000
	s_addc_u32 s63, s63, 0
	s_mov_b32 m0, s67
	v_lshl_add_u64 v[246:247], s[62:63], 0, v[148:149]
	ds_read_b128 v[196:199], v183 offset:32768
	ds_read_b128 v[210:213], v183 offset:33792
	ds_read_b128 v[214:217], v183 offset:34816
	ds_read_b128 v[218:221], v183 offset:35840
	ds_read_b128 v[224:227], v183 offset:36864
	ds_read_b128 v[228:231], v183 offset:37888
	ds_read_b128 v[232:235], v183 offset:38912
	ds_read_b128 v[236:239], v183 offset:39936
	global_load_lds_dwordx4 v[246:247], off
	v_lshl_add_u64 v[246:247], s[62:63], 0, v[146:147]
	s_mov_b32 m0, s68
	s_nop 0
	global_load_lds_dwordx4 v[246:247], off
	s_waitcnt vmcnt(8)
	s_waitcnt lgkmcnt(0)
	s_setprio 1
	s_barrier
	s_waitcnt lgkmcnt(0)
	v_mfma_f32_16x16x32_bf16 v[124:127], v[128:131], v[196:199], v[124:127]
	v_mfma_f32_16x16x32_bf16 v[120:123], v[136:139], v[196:199], v[120:123]
	v_mfma_f32_16x16x32_bf16 v[108:111], v[128:131], v[214:217], v[108:111]
	v_mfma_f32_16x16x32_bf16 v[104:107], v[136:139], v[214:217], v[104:107]
	v_mfma_f32_16x16x32_bf16 v[92:95], v[128:131], v[224:227], v[92:95]
	v_mfma_f32_16x16x32_bf16 v[88:91], v[136:139], v[224:227], v[88:91]
	v_mfma_f32_16x16x32_bf16 v[76:79], v[128:131], v[232:235], v[76:79]
	v_mfma_f32_16x16x32_bf16 v[72:75], v[136:139], v[232:235], v[72:75]
	v_mfma_f32_16x16x32_bf16 v[124:127], v[132:135], v[210:213], v[124:127]
	v_mfma_f32_16x16x32_bf16 v[120:123], v[140:143], v[210:213], v[120:123]
	v_mfma_f32_16x16x32_bf16 v[108:111], v[132:135], v[218:221], v[108:111]
	v_mfma_f32_16x16x32_bf16 v[104:107], v[140:143], v[218:221], v[104:107]
	v_mfma_f32_16x16x32_bf16 v[92:95], v[132:135], v[228:231], v[92:95]
	v_mfma_f32_16x16x32_bf16 v[88:91], v[140:143], v[228:231], v[88:91]
	v_mfma_f32_16x16x32_bf16 v[76:79], v[132:135], v[236:239], v[76:79]
	v_mfma_f32_16x16x32_bf16 v[72:75], v[140:143], v[236:239], v[72:75]
	s_setprio 0
	s_setprio 1
	v_mfma_f32_16x16x32_bf16 v[116:119], v[174:177], v[196:199], v[116:119]
	v_mfma_f32_16x16x32_bf16 v[112:115], v[188:191], v[196:199], v[112:115]
	v_mfma_f32_16x16x32_bf16 v[100:103], v[174:177], v[214:217], v[100:103]
	v_mfma_f32_16x16x32_bf16 v[96:99], v[188:191], v[214:217], v[96:99]
	v_mfma_f32_16x16x32_bf16 v[84:87], v[174:177], v[224:227], v[84:87]
	v_mfma_f32_16x16x32_bf16 v[80:83], v[188:191], v[224:227], v[80:83]
	v_mfma_f32_16x16x32_bf16 v[68:71], v[174:177], v[232:235], v[68:71]
	v_mfma_f32_16x16x32_bf16 v[64:67], v[188:191], v[232:235], v[64:67]
	v_mfma_f32_16x16x32_bf16 v[116:119], v[184:187], v[210:213], v[116:119]
	v_mfma_f32_16x16x32_bf16 v[112:115], v[192:195], v[210:213], v[112:115]
	v_mfma_f32_16x16x32_bf16 v[100:103], v[184:187], v[218:221], v[100:103]
	v_mfma_f32_16x16x32_bf16 v[96:99], v[192:195], v[218:221], v[96:99]
	v_mfma_f32_16x16x32_bf16 v[84:87], v[184:187], v[228:231], v[84:87]
	v_mfma_f32_16x16x32_bf16 v[80:83], v[192:195], v[228:231], v[80:83]
	v_mfma_f32_16x16x32_bf16 v[68:71], v[184:187], v[236:239], v[68:71]
	v_mfma_f32_16x16x32_bf16 v[64:67], v[192:195], v[236:239], v[64:67]
	s_setprio 0
	s_barrier
	s_add_i32 s62, s83, s8
	v_lshl_add_u64 v[178:179], v[178:179], 0, s[22:23]
	s_mov_b32 m0, s62
	ds_read_b128 v[196:199], v183 offset:49152
	ds_read_b128 v[210:213], v183 offset:50176
	ds_read_b128 v[214:217], v183 offset:51200
	ds_read_b128 v[218:221], v183 offset:52224
	ds_read_b128 v[224:227], v183 offset:53248
	ds_read_b128 v[228:231], v183 offset:54272
	ds_read_b128 v[232:235], v183 offset:55296
	ds_read_b128 v[236:239], v183 offset:56320
	global_load_lds_dwordx4 v[178:179], off
	s_add_i32 m0, s62, 0x2000
	s_add_u32 s44, s44, 0x20080
	v_lshl_add_u64 v[178:179], v[240:241], 0, s[22:23]
	s_addc_u32 s45, s45, 0
	s_add_i32 s62, s84, s8
	global_load_lds_dwordx4 v[178:179], off
	v_lshl_add_u64 v[178:179], s[44:45], 0, v[152:153]
	s_mov_b32 m0, s62
	s_nop 0
	global_load_lds_dwordx4 v[178:179], off
	v_lshl_add_u64 v[178:179], s[44:45], 0, v[144:145]
	s_add_i32 m0, s62, 0x2000
	s_nop 0
	global_load_lds_dwordx4 v[178:179], off
	v_lshl_add_u64 v[178:179], v[242:243], 0, s[22:23]
	s_mov_b32 m0, s69
	s_nop 0
	global_load_lds_dwordx4 v[178:179], off
	v_lshl_add_u64 v[178:179], v[244:245], 0, s[22:23]
	s_mov_b32 m0, s74
	s_nop 0
	global_load_lds_dwordx4 v[178:179], off
	s_waitcnt vmcnt(8)
	s_waitcnt lgkmcnt(0)
	s_setprio 1
	s_barrier
	s_waitcnt lgkmcnt(0)
	v_mfma_f32_16x16x32_bf16 v[60:63], v[128:131], v[196:199], v[60:63]
	v_mfma_f32_16x16x32_bf16 v[56:59], v[136:139], v[196:199], v[56:59]
	v_mfma_f32_16x16x32_bf16 v[44:47], v[128:131], v[214:217], v[44:47]
	v_mfma_f32_16x16x32_bf16 v[40:43], v[136:139], v[214:217], v[40:43]
	v_mfma_f32_16x16x32_bf16 v[28:31], v[128:131], v[224:227], v[28:31]
	v_mfma_f32_16x16x32_bf16 v[24:27], v[136:139], v[224:227], v[24:27]
	v_mfma_f32_16x16x32_bf16 v[12:15], v[128:131], v[232:235], v[12:15]
	v_mfma_f32_16x16x32_bf16 v[8:11], v[136:139], v[232:235], v[8:11]
	v_mfma_f32_16x16x32_bf16 v[60:63], v[132:135], v[210:213], v[60:63]
	v_mfma_f32_16x16x32_bf16 v[56:59], v[140:143], v[210:213], v[56:59]
	v_mfma_f32_16x16x32_bf16 v[44:47], v[132:135], v[218:221], v[44:47]
	v_mfma_f32_16x16x32_bf16 v[40:43], v[140:143], v[218:221], v[40:43]
	v_mfma_f32_16x16x32_bf16 v[28:31], v[132:135], v[228:231], v[28:31]
	v_mfma_f32_16x16x32_bf16 v[24:27], v[140:143], v[228:231], v[24:27]
	v_mfma_f32_16x16x32_bf16 v[12:15], v[132:135], v[236:239], v[12:15]
	v_mfma_f32_16x16x32_bf16 v[8:11], v[140:143], v[236:239], v[8:11]
	s_setprio 0
	s_setprio 1
	v_mfma_f32_16x16x32_bf16 v[52:55], v[174:177], v[196:199], v[52:55]
	v_mfma_f32_16x16x32_bf16 v[48:51], v[188:191], v[196:199], v[48:51]
	v_mfma_f32_16x16x32_bf16 v[36:39], v[174:177], v[214:217], v[36:39]
	v_mfma_f32_16x16x32_bf16 v[32:35], v[188:191], v[214:217], v[32:35]
	v_mfma_f32_16x16x32_bf16 v[20:23], v[174:177], v[224:227], v[20:23]
	v_mfma_f32_16x16x32_bf16 v[16:19], v[188:191], v[224:227], v[16:19]
	v_mfma_f32_16x16x32_bf16 v[4:7], v[174:177], v[232:235], v[4:7]
	v_mfma_f32_16x16x32_bf16 v[0:3], v[188:191], v[232:235], v[0:3]
	v_mfma_f32_16x16x32_bf16 v[52:55], v[184:187], v[210:213], v[52:55]
	v_mfma_f32_16x16x32_bf16 v[48:51], v[192:195], v[210:213], v[48:51]
	v_mfma_f32_16x16x32_bf16 v[36:39], v[184:187], v[218:221], v[36:39]
	v_mfma_f32_16x16x32_bf16 v[32:35], v[192:195], v[218:221], v[32:35]
	v_mfma_f32_16x16x32_bf16 v[20:23], v[184:187], v[228:231], v[20:23]
	v_mfma_f32_16x16x32_bf16 v[16:19], v[192:195], v[228:231], v[16:19]
	v_mfma_f32_16x16x32_bf16 v[4:7], v[184:187], v[236:239], v[4:7]
	v_mfma_f32_16x16x32_bf16 v[0:3], v[192:195], v[236:239], v[0:3]
	s_setprio 0
	s_barrier
	s_add_i32 s82, s82, 2
	s_add_u32 s80, s80, 0x100
	s_addc_u32 s81, s81, 0
	s_add_u32 s60, s60, 0x100
	s_addc_u32 s61, s61, 0
	s_cmp_gt_u32 s82, 5
	s_cbranch_scc0 .LBB0_725
	s_and_b64 vcc, exec, s[16:17]
	s_cbranch_vccz .LBB0_728
	s_barrier

.LBB0_822:
	s_add_u32 s62, s60, 0xfffc0080
	s_addc_u32 s63, s61, -1
	s_add_i32 s86, 0, 0x10000
	s_cmp_eq_u32 s85, 12
	s_cselect_b32 s67, s21, s63
	s_cselect_b32 s66, s81, s62
	s_cselect_b32 s63, s19, s84
	s_cselect_b32 s62, s82, s83
	s_add_i32 s89, 0, 0x14000
	v_add_u32_e32 v124, s86, v210
	v_add_u32_e32 v186, s89, v210
	ds_read_b128 v[112:115], v124
	ds_read_b128 v[116:119], v124 offset:1024
	ds_read_b128 v[120:123], v124 offset:2048
	ds_read_b128 v[124:127], v124 offset:3072
	ds_read_b128 v[132:135], v186
	ds_read_b128 v[140:143], v186 offset:1024
	ds_read_b128 v[182:185], v186 offset:2048
	ds_read_b128 v[186:189], v186 offset:3072
	v_lshl_add_u64 v[198:199], s[60:61], 0, v[180:181]
	s_add_i32 m0, s68, 0xc000
	ds_read_b128 v[190:193], v212
	ds_read_b128 v[194:197], v212 offset:1024
	ds_read_b128 v[214:217], v212 offset:2048
	ds_read_b128 v[218:221], v212 offset:3072
	ds_read_b128 v[224:227], v212 offset:4096
	ds_read_b128 v[228:231], v212 offset:5120
	ds_read_b128 v[232:235], v212 offset:6144
	ds_read_b128 v[236:239], v212 offset:7168
	global_load_lds_dwordx4 v[198:199], off
	v_lshl_add_u64 v[198:199], s[60:61], 0, v[178:179]
	s_add_i32 m0, s68, 0xe000
	s_nop 0
	global_load_lds_dwordx4 v[198:199], off
	s_waitcnt vmcnt(8)
	s_waitcnt lgkmcnt(0)
	s_setprio 1
	s_barrier
	s_waitcnt lgkmcnt(0)
	v_mfma_f32_16x16x32_bf16 v[148:151], v[112:115], v[190:193], v[148:151]
	v_mfma_f32_16x16x32_bf16 v[144:147], v[120:123], v[190:193], v[144:147]
	v_mfma_f32_16x16x32_bf16 v[108:111], v[112:115], v[214:217], v[108:111]
	v_mfma_f32_16x16x32_bf16 v[104:107], v[120:123], v[214:217], v[104:107]
	v_mfma_f32_16x16x32_bf16 v[92:95], v[112:115], v[224:227], v[92:95]
	v_mfma_f32_16x16x32_bf16 v[88:91], v[120:123], v[224:227], v[88:91]
	v_mfma_f32_16x16x32_bf16 v[76:79], v[112:115], v[232:235], v[76:79]
	v_mfma_f32_16x16x32_bf16 v[72:75], v[120:123], v[232:235], v[72:75]
	v_mfma_f32_16x16x32_bf16 v[148:151], v[116:119], v[194:197], v[148:151]
	v_mfma_f32_16x16x32_bf16 v[144:147], v[124:127], v[194:197], v[144:147]
	v_mfma_f32_16x16x32_bf16 v[108:111], v[116:119], v[218:221], v[108:111]
	v_mfma_f32_16x16x32_bf16 v[104:107], v[124:127], v[218:221], v[104:107]
	v_mfma_f32_16x16x32_bf16 v[92:95], v[116:119], v[228:231], v[92:95]
	v_mfma_f32_16x16x32_bf16 v[88:91], v[124:127], v[228:231], v[88:91]
	v_mfma_f32_16x16x32_bf16 v[76:79], v[116:119], v[236:239], v[76:79]
	v_mfma_f32_16x16x32_bf16 v[72:75], v[124:127], v[236:239], v[72:75]
	s_setprio 0
	s_setprio 1
	v_mfma_f32_16x16x32_bf16 v[136:139], v[132:135], v[190:193], v[136:139]
	v_mfma_f32_16x16x32_bf16 v[128:131], v[182:185], v[190:193], v[128:131]
	v_mfma_f32_16x16x32_bf16 v[100:103], v[132:135], v[214:217], v[100:103]
	v_mfma_f32_16x16x32_bf16 v[96:99], v[182:185], v[214:217], v[96:99]
	v_mfma_f32_16x16x32_bf16 v[84:87], v[132:135], v[224:227], v[84:87]
	v_mfma_f32_16x16x32_bf16 v[80:83], v[182:185], v[224:227], v[80:83]
	v_mfma_f32_16x16x32_bf16 v[68:71], v[132:135], v[232:235], v[68:71]
	v_mfma_f32_16x16x32_bf16 v[64:67], v[182:185], v[232:235], v[64:67]
	v_mfma_f32_16x16x32_bf16 v[136:139], v[140:143], v[194:197], v[136:139]
	v_mfma_f32_16x16x32_bf16 v[128:131], v[186:189], v[194:197], v[128:131]
	v_mfma_f32_16x16x32_bf16 v[100:103], v[140:143], v[218:221], v[100:103]
	v_mfma_f32_16x16x32_bf16 v[96:99], v[186:189], v[218:221], v[96:99]
	v_mfma_f32_16x16x32_bf16 v[84:87], v[140:143], v[228:231], v[84:87]
	v_mfma_f32_16x16x32_bf16 v[80:83], v[186:189], v[228:231], v[80:83]
	v_mfma_f32_16x16x32_bf16 v[68:71], v[140:143], v[236:239], v[68:71]
	v_mfma_f32_16x16x32_bf16 v[64:67], v[186:189], v[236:239], v[64:67]
	s_setprio 0
	s_barrier
	s_add_i32 s86, s86, s59
	v_lshl_add_u64 v[198:199], s[62:63], 0, v[152:153]
	s_mov_b32 m0, s86
	ds_read_b128 v[190:193], v212 offset:16384
	ds_read_b128 v[194:197], v212 offset:17408
	ds_read_b128 v[214:217], v212 offset:18432
	ds_read_b128 v[218:221], v212 offset:19456
	ds_read_b128 v[224:227], v212 offset:20480
	ds_read_b128 v[228:231], v212 offset:21504
	ds_read_b128 v[232:235], v212 offset:22528
	ds_read_b128 v[236:239], v212 offset:23552
	global_load_lds_dwordx4 v[198:199], off
	s_add_i32 m0, s86, 0x2000
	s_add_u32 s86, s62, 0x40000
	v_lshl_add_u64 v[240:241], s[62:63], 0, v[172:173]
	s_addc_u32 s87, s63, 0
	s_add_i32 s89, s89, s59
	global_load_lds_dwordx4 v[240:241], off
	v_lshl_add_u64 v[242:243], s[86:87], 0, v[152:153]
	s_mov_b32 m0, s89
	v_lshl_add_u64 v[244:245], s[66:67], 0, v[174:175]
	global_load_lds_dwordx4 v[242:243], off
	v_lshl_add_u64 v[242:243], s[86:87], 0, v[172:173]
	s_add_i32 m0, s89, 0x2000
	s_nop 0
	global_load_lds_dwordx4 v[242:243], off
	v_lshl_add_u64 v[242:243], s[66:67], 0, v[176:177]
	s_mov_b32 m0, s68
	s_nop 0
	global_load_lds_dwordx4 v[242:243], off
	s_mov_b32 m0, s69
	s_nop 0
	global_load_lds_dwordx4 v[244:245], off
	s_waitcnt vmcnt(8)
	s_waitcnt lgkmcnt(0)
	s_setprio 1
	s_barrier
	s_waitcnt lgkmcnt(0)
	v_mfma_f32_16x16x32_bf16 v[60:63], v[112:115], v[190:193], v[60:63]
	v_mfma_f32_16x16x32_bf16 v[56:59], v[120:123], v[190:193], v[56:59]
	v_mfma_f32_16x16x32_bf16 v[44:47], v[112:115], v[214:217], v[44:47]
	v_mfma_f32_16x16x32_bf16 v[40:43], v[120:123], v[214:217], v[40:43]
	v_mfma_f32_16x16x32_bf16 v[28:31], v[112:115], v[224:227], v[28:31]
	v_mfma_f32_16x16x32_bf16 v[24:27], v[120:123], v[224:227], v[24:27]
	v_mfma_f32_16x16x32_bf16 v[12:15], v[112:115], v[232:235], v[12:15]
	v_mfma_f32_16x16x32_bf16 v[8:11], v[120:123], v[232:235], v[8:11]
	v_mfma_f32_16x16x32_bf16 v[60:63], v[116:119], v[194:197], v[60:63]
	v_mfma_f32_16x16x32_bf16 v[56:59], v[124:127], v[194:197], v[56:59]
	v_mfma_f32_16x16x32_bf16 v[44:47], v[116:119], v[218:221], v[44:47]
	v_mfma_f32_16x16x32_bf16 v[40:43], v[124:127], v[218:221], v[40:43]
	v_mfma_f32_16x16x32_bf16 v[28:31], v[116:119], v[228:231], v[28:31]
	v_mfma_f32_16x16x32_bf16 v[24:27], v[124:127], v[228:231], v[24:27]
	v_mfma_f32_16x16x32_bf16 v[12:15], v[116:119], v[236:239], v[12:15]
	v_mfma_f32_16x16x32_bf16 v[8:11], v[124:127], v[236:239], v[8:11]
	s_setprio 0
	s_setprio 1
	v_mfma_f32_16x16x32_bf16 v[52:55], v[132:135], v[190:193], v[52:55]
	v_mfma_f32_16x16x32_bf16 v[48:51], v[182:185], v[190:193], v[48:51]
	v_mfma_f32_16x16x32_bf16 v[36:39], v[132:135], v[214:217], v[36:39]
	v_mfma_f32_16x16x32_bf16 v[32:35], v[182:185], v[214:217], v[32:35]
	v_mfma_f32_16x16x32_bf16 v[20:23], v[132:135], v[224:227], v[20:23]
	v_mfma_f32_16x16x32_bf16 v[16:19], v[182:185], v[224:227], v[16:19]
	v_mfma_f32_16x16x32_bf16 v[4:7], v[132:135], v[232:235], v[4:7]
	v_mfma_f32_16x16x32_bf16 v[0:3], v[182:185], v[232:235], v[0:3]
	v_mfma_f32_16x16x32_bf16 v[52:55], v[140:143], v[194:197], v[52:55]
	v_mfma_f32_16x16x32_bf16 v[48:51], v[186:189], v[194:197], v[48:51]
	v_mfma_f32_16x16x32_bf16 v[36:39], v[140:143], v[218:221], v[36:39]
	v_mfma_f32_16x16x32_bf16 v[32:35], v[186:189], v[218:221], v[32:35]
	v_mfma_f32_16x16x32_bf16 v[20:23], v[140:143], v[228:231], v[20:23]
	v_mfma_f32_16x16x32_bf16 v[16:19], v[186:189], v[228:231], v[16:19]
	v_mfma_f32_16x16x32_bf16 v[4:7], v[140:143], v[236:239], v[4:7]
	v_mfma_f32_16x16x32_bf16 v[0:3], v[186:189], v[236:239], v[0:3]
	s_setprio 0
	s_barrier
	s_add_i32 s86, 0, 0x18000
	s_add_i32 s87, 0, 0x1c000
	v_add_u32_e32 v124, s86, v210
	v_add_u32_e32 v186, s87, v210
	ds_read_b128 v[112:115], v124
	ds_read_b128 v[116:119], v124 offset:1024
	ds_read_b128 v[120:123], v124 offset:2048
	ds_read_b128 v[124:127], v124 offset:3072
	ds_read_b128 v[132:135], v186
	ds_read_b128 v[140:143], v186 offset:1024
	ds_read_b128 v[182:185], v186 offset:2048
	ds_read_b128 v[186:189], v186 offset:3072
	s_add_u32 s66, s66, 0x40000
	s_addc_u32 s67, s67, 0
	s_mov_b32 m0, s74
	v_lshl_add_u64 v[246:247], s[66:67], 0, v[176:177]
	ds_read_b128 v[190:193], v212 offset:32768
	ds_read_b128 v[194:197], v212 offset:33792
	ds_read_b128 v[214:217], v212 offset:34816
	ds_read_b128 v[218:221], v212 offset:35840
	ds_read_b128 v[224:227], v212 offset:36864
	ds_read_b128 v[228:231], v212 offset:37888
	ds_read_b128 v[232:235], v212 offset:38912
	ds_read_b128 v[236:239], v212 offset:39936
	global_load_lds_dwordx4 v[246:247], off
	v_lshl_add_u64 v[246:247], s[66:67], 0, v[174:175]
	s_mov_b32 m0, s75
	s_nop 0
	global_load_lds_dwordx4 v[246:247], off
	s_waitcnt vmcnt(8)
	s_waitcnt lgkmcnt(0)
	s_setprio 1
	s_barrier
	s_waitcnt lgkmcnt(0)
	v_mfma_f32_16x16x32_bf16 v[148:151], v[112:115], v[190:193], v[148:151]
	v_mfma_f32_16x16x32_bf16 v[144:147], v[120:123], v[190:193], v[144:147]
	v_mfma_f32_16x16x32_bf16 v[108:111], v[112:115], v[214:217], v[108:111]
	v_mfma_f32_16x16x32_bf16 v[104:107], v[120:123], v[214:217], v[104:107]
	v_mfma_f32_16x16x32_bf16 v[92:95], v[112:115], v[224:227], v[92:95]
	v_mfma_f32_16x16x32_bf16 v[88:91], v[120:123], v[224:227], v[88:91]
	v_mfma_f32_16x16x32_bf16 v[76:79], v[112:115], v[232:235], v[76:79]
	v_mfma_f32_16x16x32_bf16 v[72:75], v[120:123], v[232:235], v[72:75]
	v_mfma_f32_16x16x32_bf16 v[148:151], v[116:119], v[194:197], v[148:151]
	v_mfma_f32_16x16x32_bf16 v[144:147], v[124:127], v[194:197], v[144:147]
	v_mfma_f32_16x16x32_bf16 v[108:111], v[116:119], v[218:221], v[108:111]
	v_mfma_f32_16x16x32_bf16 v[104:107], v[124:127], v[218:221], v[104:107]
	v_mfma_f32_16x16x32_bf16 v[92:95], v[116:119], v[228:231], v[92:95]
	v_mfma_f32_16x16x32_bf16 v[88:91], v[124:127], v[228:231], v[88:91]
	v_mfma_f32_16x16x32_bf16 v[76:79], v[116:119], v[236:239], v[76:79]
	v_mfma_f32_16x16x32_bf16 v[72:75], v[124:127], v[236:239], v[72:75]
	s_setprio 0
	s_setprio 1
	v_mfma_f32_16x16x32_bf16 v[136:139], v[132:135], v[190:193], v[136:139]
	v_mfma_f32_16x16x32_bf16 v[128:131], v[182:185], v[190:193], v[128:131]
	v_mfma_f32_16x16x32_bf16 v[100:103], v[132:135], v[214:217], v[100:103]
	v_mfma_f32_16x16x32_bf16 v[96:99], v[182:185], v[214:217], v[96:99]
	v_mfma_f32_16x16x32_bf16 v[84:87], v[132:135], v[224:227], v[84:87]
	v_mfma_f32_16x16x32_bf16 v[80:83], v[182:185], v[224:227], v[80:83]
	v_mfma_f32_16x16x32_bf16 v[68:71], v[132:135], v[232:235], v[68:71]
	v_mfma_f32_16x16x32_bf16 v[64:67], v[182:185], v[232:235], v[64:67]
	v_mfma_f32_16x16x32_bf16 v[136:139], v[140:143], v[194:197], v[136:139]
	v_mfma_f32_16x16x32_bf16 v[128:131], v[186:189], v[194:197], v[128:131]
	v_mfma_f32_16x16x32_bf16 v[100:103], v[140:143], v[218:221], v[100:103]
	v_mfma_f32_16x16x32_bf16 v[96:99], v[186:189], v[218:221], v[96:99]
	v_mfma_f32_16x16x32_bf16 v[84:87], v[140:143], v[228:231], v[84:87]
	v_mfma_f32_16x16x32_bf16 v[80:83], v[186:189], v[228:231], v[80:83]
	v_mfma_f32_16x16x32_bf16 v[68:71], v[140:143], v[236:239], v[68:71]
	v_mfma_f32_16x16x32_bf16 v[64:67], v[186:189], v[236:239], v[64:67]
	s_setprio 0
	s_barrier
	s_add_i32 s66, s86, s59
	v_lshl_add_u64 v[198:199], v[198:199], 0, s[22:23]
	s_mov_b32 m0, s66
	ds_read_b128 v[190:193], v212 offset:49152
	ds_read_b128 v[194:197], v212 offset:50176
	ds_read_b128 v[214:217], v212 offset:51200
	ds_read_b128 v[218:221], v212 offset:52224
	ds_read_b128 v[224:227], v212 offset:53248
	ds_read_b128 v[228:231], v212 offset:54272
	ds_read_b128 v[232:235], v212 offset:55296
	ds_read_b128 v[236:239], v212 offset:56320
	global_load_lds_dwordx4 v[198:199], off
	s_add_i32 m0, s66, 0x2000
	s_add_u32 s62, s62, 0x40080
	v_lshl_add_u64 v[198:199], v[240:241], 0, s[22:23]
	s_addc_u32 s63, s63, 0
	s_add_i32 s66, s87, s59
	global_load_lds_dwordx4 v[198:199], off
	v_lshl_add_u64 v[198:199], s[62:63], 0, v[152:153]
	s_mov_b32 m0, s66
	s_nop 0
	global_load_lds_dwordx4 v[198:199], off
	v_lshl_add_u64 v[198:199], s[62:63], 0, v[172:173]
	s_add_i32 m0, s66, 0x2000
	s_nop 0
	global_load_lds_dwordx4 v[198:199], off
	v_lshl_add_u64 v[198:199], v[242:243], 0, s[22:23]
	s_mov_b32 m0, s77
	s_nop 0
	global_load_lds_dwordx4 v[198:199], off
	v_lshl_add_u64 v[198:199], v[244:245], 0, s[22:23]
	s_mov_b32 m0, s78
	s_nop 0
	global_load_lds_dwordx4 v[198:199], off
	s_waitcnt vmcnt(8)
	s_waitcnt lgkmcnt(0)
	s_setprio 1
	s_barrier
	s_waitcnt lgkmcnt(0)
	v_mfma_f32_16x16x32_bf16 v[60:63], v[112:115], v[190:193], v[60:63]
	v_mfma_f32_16x16x32_bf16 v[56:59], v[120:123], v[190:193], v[56:59]
	v_mfma_f32_16x16x32_bf16 v[44:47], v[112:115], v[214:217], v[44:47]
	v_mfma_f32_16x16x32_bf16 v[40:43], v[120:123], v[214:217], v[40:43]
	v_mfma_f32_16x16x32_bf16 v[28:31], v[112:115], v[224:227], v[28:31]
	v_mfma_f32_16x16x32_bf16 v[24:27], v[120:123], v[224:227], v[24:27]
	v_mfma_f32_16x16x32_bf16 v[12:15], v[112:115], v[232:235], v[12:15]
	v_mfma_f32_16x16x32_bf16 v[8:11], v[120:123], v[232:235], v[8:11]
	v_mfma_f32_16x16x32_bf16 v[60:63], v[116:119], v[194:197], v[60:63]
	v_mfma_f32_16x16x32_bf16 v[56:59], v[124:127], v[194:197], v[56:59]
	v_mfma_f32_16x16x32_bf16 v[44:47], v[116:119], v[218:221], v[44:47]
	v_mfma_f32_16x16x32_bf16 v[40:43], v[124:127], v[218:221], v[40:43]
	v_mfma_f32_16x16x32_bf16 v[28:31], v[116:119], v[228:231], v[28:31]
	v_mfma_f32_16x16x32_bf16 v[24:27], v[124:127], v[228:231], v[24:27]
	v_mfma_f32_16x16x32_bf16 v[12:15], v[116:119], v[236:239], v[12:15]
	v_mfma_f32_16x16x32_bf16 v[8:11], v[124:127], v[236:239], v[8:11]
	s_setprio 0
	s_setprio 1
	v_mfma_f32_16x16x32_bf16 v[52:55], v[132:135], v[190:193], v[52:55]
	v_mfma_f32_16x16x32_bf16 v[48:51], v[182:185], v[190:193], v[48:51]
	v_mfma_f32_16x16x32_bf16 v[36:39], v[132:135], v[214:217], v[36:39]
	v_mfma_f32_16x16x32_bf16 v[32:35], v[182:185], v[214:217], v[32:35]
	v_mfma_f32_16x16x32_bf16 v[20:23], v[132:135], v[224:227], v[20:23]
	v_mfma_f32_16x16x32_bf16 v[16:19], v[182:185], v[224:227], v[16:19]
	v_mfma_f32_16x16x32_bf16 v[4:7], v[132:135], v[232:235], v[4:7]
	v_mfma_f32_16x16x32_bf16 v[0:3], v[182:185], v[232:235], v[0:3]
	v_mfma_f32_16x16x32_bf16 v[52:55], v[140:143], v[194:197], v[52:55]
	v_mfma_f32_16x16x32_bf16 v[48:51], v[186:189], v[194:197], v[48:51]
	v_mfma_f32_16x16x32_bf16 v[36:39], v[140:143], v[218:221], v[36:39]
	v_mfma_f32_16x16x32_bf16 v[32:35], v[186:189], v[218:221], v[32:35]
	v_mfma_f32_16x16x32_bf16 v[20:23], v[140:143], v[228:231], v[20:23]
	v_mfma_f32_16x16x32_bf16 v[16:19], v[186:189], v[228:231], v[16:19]
	v_mfma_f32_16x16x32_bf16 v[4:7], v[140:143], v[236:239], v[4:7]
	v_mfma_f32_16x16x32_bf16 v[0:3], v[186:189], v[236:239], v[0:3]
	s_setprio 0
	s_barrier
	s_add_i32 s85, s85, 2
	s_add_u32 s83, s83, 0x100
	s_addc_u32 s84, s84, 0
	s_add_u32 s60, s60, 0x100
	s_addc_u32 s61, s61, 0
	s_cmp_gt_u32 s85, 13
	s_cbranch_scc0 .LBB0_822
	s_and_b64 vcc, exec, s[16:17]
	s_cbranch_vccz .LBB0_825
	s_barrier
